# redundant post-barrier s_waitcnt lgkmcnt(0) removed from the MFMA segment heads of the 6 K-loops (on top of v29)
# baseline (speedup 1.0000x reference)
;     __device__ __forceinline__ bool next(int i, Unit& u) const { if (i > 0 || c >= nitems) return false; u.pm = 64; u.pn = c % npn; u.k0 = (c / npn) * kslice; return true; }
; #define PG8_STAGE(bufoff, gbase, voff) do { _Pragma("unroll") for (int _i = 0; _i < 2; ++_i) \
;         __builtin_amdgcn_global_load_lds((const unsigned*)((const char*)(gbase) + (voff)[_i]), (PG8_LAS unsigned*)(lds + (bufoff) + ldsw + _i * 8192), 16, 0, 0); } while (0)
; #define PG8_LDA(dst, b, h) do { _Pragma("unroll") for (int m = 0; m < 4; ++m) _Pragma("unroll") for (int k = 0; k < 2; ++k) dst[m][k] = *(const PG8_LAS bf16x8*)(lds + PG8_SA(b, h) + aoff + m * 2048 + k * 1024); } while (0)
; #define PG8_LDB(dst, b, h) do { _Pragma("unroll") for (int n = 0; n < 2; ++n) _Pragma("unroll") for (int k = 0; k < 2; ++k) dst[n][k] = *(const PG8_LAS bf16x8*)(lds + PG8_SB(b, h) + boff + n * 2048 + k * 1024); } while (0)
; #define PG8_WAIT_V(n) asm volatile("s_waitcnt vmcnt(" #n ")" ::: "memory")
; template <class Epi, class Sched, bool ALIGN_EPI = false, bool SP2 = false>
; __device__ __forceinline__ void gemm_phase(PG8_LAS unsigned char* lds, const Gemm g, const Sched& S, const Epi& E) {
;     ...
;         const bool has_next = S.next(ui + 1, nxt);
;         const char* nA = has_next ? (const char*)g.A + (size_t)nxt.pm * tstep + (size_t)nxt.k0 * 2 : cA; const char* nB = has_next ? (const char*)g.Bt + (size_t)nxt.pn * tstep + (size_t)nxt.k0 * 2 : cB;
;         for (int t = 0; t < nt; t += 2) {
;             const bool last = (t == nt - 2);
;             const char* a1 = cA + (size_t)(t + 1) * kstep;
;             const char* a2 = last ? nA : cA + (size_t)(t + 2) * kstep; const char* b2 = last ? nB : cB + (size_t)(t + 2) * kstep;
;             const char* a3 = a2 + kstep; const char* b3 = b2 + kstep;
;             if (last && has_next) S.a_ready(nxt);
;             if constexpr (SP2) {
;             PG8_LDB(B0, 0, 0); PG8_LDB(B1, 0, 1); PG8_SCHED; PG8_LDA(At, 0, 0); PG8_STAGE(PG8_SA(1, 1), a1 + hstep, voffA);
;             PG8_WAIT_V(8); PG8_WAIT_L(0); PG8_BAR; PG8_MMA(0, 0, At, B0); PG8_MMA(0, 1, At, B1); PG8_BAR; PG8_SCHED;
;             PG8_LDA(At, 0, 1); PG8_STAGE(PG8_SB(0, 0), b2, voffB); PG8_STAGE(PG8_SB(0, 1), b2 + hstep, voffB); PG8_STAGE(PG8_SA(0, 0), a2, voffA);
;             PG8_WAIT_V(8); PG8_WAIT_L(0); PG8_BAR; PG8_MMA(1, 0, At, B0); PG8_MMA(1, 1, At, B1); PG8_BAR; PG8_SCHED;
.Lsp_skip_6:
.LBB0_192:
	ds_read_b128 v[162:165], v158
	ds_read_b128 v[166:169], v158 offset:1024
	ds_read_b128 v[170:173], v158 offset:2048
	ds_read_b128 v[174:177], v158 offset:3072
	ds_read_b128 v[188:191], v159
	ds_read_b128 v[196:199], v159 offset:1024
	ds_read_b128 v[200:203], v159 offset:2048
	ds_read_b128 v[204:207], v159 offset:3072
	s_add_u32 s55, s66, 0xfff80080
	s_addc_u32 s56, s67, -1
	s_cmp_eq_u32 s54, 28
	s_cselect_b32 s71, s19, s56
	s_cselect_b32 s70, s50, s55
	s_cselect_b32 s69, s17, s53
	s_cselect_b32 s68, s51, s52
	s_add_i32 m0, s37, 0xc000
	ds_read_b128 v[208:211], v161
	ds_read_b128 v[212:215], v161 offset:1024
	ds_read_b128 v[216:219], v161 offset:2048
	ds_read_b128 v[220:223], v161 offset:3072
	ds_read_b128 v[224:227], v161 offset:4096
	ds_read_b128 v[228:231], v161 offset:5120
	ds_read_b128 v[232:235], v161 offset:6144
	ds_read_b128 v[236:239], v161 offset:7168
	global_load_lds_dwordx4 v128, s[66:67]
	s_add_i32 m0, s37, 0xe000
	s_nop 0
	global_load_lds_dwordx4 v130, s[66:67]
	s_waitcnt vmcnt(8)
	s_waitcnt lgkmcnt(0)
	s_barrier
	v_mfma_f32_16x16x32_bf16 v[124:127], v[162:165], v[208:211], v[124:127]
	v_mfma_f32_16x16x32_bf16 v[124:127], v[166:169], v[212:215], v[124:127]
	v_mfma_f32_16x16x32_bf16 v[116:119], v[174:177], v[212:215], v[116:119]
	v_mfma_f32_16x16x32_bf16 v[116:119], v[170:173], v[208:211], v[116:119]
	v_mfma_f32_16x16x32_bf16 v[100:103], v[170:173], v[216:219], v[100:103]
	v_mfma_f32_16x16x32_bf16 v[100:103], v[174:177], v[220:223], v[100:103]
	v_mfma_f32_16x16x32_bf16 v[108:111], v[166:169], v[220:223], v[108:111]
	v_mfma_f32_16x16x32_bf16 v[108:111], v[162:165], v[216:219], v[108:111]
	v_mfma_f32_16x16x32_bf16 v[92:95], v[162:165], v[224:227], v[92:95]
	v_mfma_f32_16x16x32_bf16 v[92:95], v[166:169], v[228:231], v[92:95]
	v_mfma_f32_16x16x32_bf16 v[84:87], v[174:177], v[228:231], v[84:87]
	v_mfma_f32_16x16x32_bf16 v[84:87], v[170:173], v[224:227], v[84:87]
	v_mfma_f32_16x16x32_bf16 v[68:71], v[170:173], v[232:235], v[68:71]
	v_mfma_f32_16x16x32_bf16 v[68:71], v[174:177], v[236:239], v[68:71]
	v_mfma_f32_16x16x32_bf16 v[76:79], v[166:169], v[236:239], v[76:79]
	v_mfma_f32_16x16x32_bf16 v[76:79], v[162:165], v[232:235], v[76:79]
	v_mfma_f32_16x16x32_bf16 v[120:123], v[188:191], v[208:211], v[120:123]
	v_mfma_f32_16x16x32_bf16 v[120:123], v[196:199], v[212:215], v[120:123]
	v_mfma_f32_16x16x32_bf16 v[112:115], v[204:207], v[212:215], v[112:115]
	v_mfma_f32_16x16x32_bf16 v[112:115], v[200:203], v[208:211], v[112:115]
	v_mfma_f32_16x16x32_bf16 v[96:99], v[200:203], v[216:219], v[96:99]
	v_mfma_f32_16x16x32_bf16 v[96:99], v[204:207], v[220:223], v[96:99]
	v_mfma_f32_16x16x32_bf16 v[104:107], v[196:199], v[220:223], v[104:107]
	v_mfma_f32_16x16x32_bf16 v[104:107], v[188:191], v[216:219], v[104:107]
	v_mfma_f32_16x16x32_bf16 v[88:91], v[188:191], v[224:227], v[88:91]
	v_mfma_f32_16x16x32_bf16 v[88:91], v[196:199], v[228:231], v[88:91]
	v_mfma_f32_16x16x32_bf16 v[80:83], v[204:207], v[228:231], v[80:83]
	v_mfma_f32_16x16x32_bf16 v[80:83], v[200:203], v[224:227], v[80:83]
	v_mfma_f32_16x16x32_bf16 v[64:67], v[200:203], v[232:235], v[64:67]
	v_mfma_f32_16x16x32_bf16 v[64:67], v[204:207], v[236:239], v[64:67]
	v_mfma_f32_16x16x32_bf16 v[72:75], v[196:199], v[236:239], v[72:75]
	v_mfma_f32_16x16x32_bf16 v[72:75], v[188:191], v[232:235], v[72:75]
	s_barrier
	s_add_u32 s98, s68, 0x80
	s_addc_u32 s99, s69, 0
	s_add_u32 s100, s70, 0x80
	s_addc_u32 s101, s71, 0
	s_add_i32 s55, s46, s36
	s_mov_b32 m0, s55
	ds_read_b128 v[208:211], v161 offset:16384
	ds_read_b128 v[212:215], v161 offset:17408
	ds_read_b128 v[216:219], v161 offset:18432
	ds_read_b128 v[220:223], v161 offset:19456
	ds_read_b128 v[224:227], v161 offset:20480
	ds_read_b128 v[228:231], v161 offset:21504
	ds_read_b128 v[232:235], v161 offset:22528
	ds_read_b128 v[236:239], v161 offset:23552
	global_load_lds_dwordx4 v152, s[68:69]
	s_add_i32 m0, s55, 0x2000
	s_add_u32 s56, s68, 0x80000
	s_addc_u32 s57, s69, 0
	s_add_i32 s55, s47, s36
	global_load_lds_dwordx4 v156, s[68:69]
	s_mov_b32 m0, s55
	s_nop 0
	global_load_lds_dwordx4 v152, s[56:57]
	s_add_i32 m0, s55, 0x2000
	s_nop 0
	global_load_lds_dwordx4 v156, s[56:57]
	s_mov_b32 m0, s37
	s_nop 0
	global_load_lds_dwordx4 v150, s[70:71]
	s_mov_b32 m0, s38
	s_nop 0
	global_load_lds_dwordx4 v154, s[70:71]
	s_waitcnt vmcnt(8)
	s_waitcnt lgkmcnt(0)
	s_barrier
	v_mfma_f32_16x16x32_bf16 v[60:63], v[162:165], v[208:211], v[60:63]
	v_mfma_f32_16x16x32_bf16 v[60:63], v[166:169], v[212:215], v[60:63]
	v_mfma_f32_16x16x32_bf16 v[52:55], v[174:177], v[212:215], v[52:55]
	v_mfma_f32_16x16x32_bf16 v[52:55], v[170:173], v[208:211], v[52:55]
	v_mfma_f32_16x16x32_bf16 v[36:39], v[170:173], v[216:219], v[36:39]
	v_mfma_f32_16x16x32_bf16 v[36:39], v[174:177], v[220:223], v[36:39]
	v_mfma_f32_16x16x32_bf16 v[44:47], v[166:169], v[220:223], v[44:47]
	v_mfma_f32_16x16x32_bf16 v[44:47], v[162:165], v[216:219], v[44:47]
	v_mfma_f32_16x16x32_bf16 v[28:31], v[162:165], v[224:227], v[28:31]
	v_mfma_f32_16x16x32_bf16 v[28:31], v[166:169], v[228:231], v[28:31]
	v_mfma_f32_16x16x32_bf16 v[20:23], v[174:177], v[228:231], v[20:23]
	v_mfma_f32_16x16x32_bf16 v[20:23], v[170:173], v[224:227], v[20:23]
	v_mfma_f32_16x16x32_bf16 v[4:7], v[170:173], v[232:235], v[4:7]
	v_mfma_f32_16x16x32_bf16 v[4:7], v[174:177], v[236:239], v[4:7]
	v_mfma_f32_16x16x32_bf16 v[12:15], v[166:169], v[236:239], v[12:15]
	v_mfma_f32_16x16x32_bf16 v[12:15], v[162:165], v[232:235], v[12:15]
	v_mfma_f32_16x16x32_bf16 v[56:59], v[188:191], v[208:211], v[56:59]
	v_mfma_f32_16x16x32_bf16 v[56:59], v[196:199], v[212:215], v[56:59]
	v_mfma_f32_16x16x32_bf16 v[48:51], v[204:207], v[212:215], v[48:51]
	v_mfma_f32_16x16x32_bf16 v[48:51], v[200:203], v[208:211], v[48:51]
	v_mfma_f32_16x16x32_bf16 v[32:35], v[200:203], v[216:219], v[32:35]
	v_mfma_f32_16x16x32_bf16 v[32:35], v[204:207], v[220:223], v[32:35]
	v_mfma_f32_16x16x32_bf16 v[40:43], v[196:199], v[220:223], v[40:43]
	v_mfma_f32_16x16x32_bf16 v[40:43], v[188:191], v[216:219], v[40:43]
	v_mfma_f32_16x16x32_bf16 v[24:27], v[188:191], v[224:227], v[24:27]
	v_mfma_f32_16x16x32_bf16 v[24:27], v[196:199], v[228:231], v[24:27]
	v_mfma_f32_16x16x32_bf16 v[16:19], v[204:207], v[228:231], v[16:19]
	v_mfma_f32_16x16x32_bf16 v[16:19], v[200:203], v[224:227], v[16:19]
	v_mfma_f32_16x16x32_bf16 v[0:3], v[200:203], v[232:235], v[0:3]
	v_mfma_f32_16x16x32_bf16 v[0:3], v[204:207], v[236:239], v[0:3]
	v_mfma_f32_16x16x32_bf16 v[8:11], v[196:199], v[236:239], v[8:11]
	v_mfma_f32_16x16x32_bf16 v[8:11], v[188:191], v[232:235], v[8:11]
	s_barrier
; #define PG8_STAGE(bufoff, gbase, voff) do { _Pragma("unroll") for (int _i = 0; _i < 2; ++_i) \
;         __builtin_amdgcn_global_load_lds((const unsigned*)((const char*)(gbase) + (voff)[_i]), (PG8_LAS unsigned*)(lds + (bufoff) + ldsw + _i * 8192), 16, 0, 0); } while (0)
; #define PG8_LDA(dst, b, h) do { _Pragma("unroll") for (int m = 0; m < 4; ++m) _Pragma("unroll") for (int k = 0; k < 2; ++k) dst[m][k] = *(const PG8_LAS bf16x8*)(lds + PG8_SA(b, h) + aoff + m * 2048 + k * 1024); } while (0)
; #define PG8_LDB(dst, b, h) do { _Pragma("unroll") for (int n = 0; n < 2; ++n) _Pragma("unroll") for (int k = 0; k < 2; ++k) dst[n][k] = *(const PG8_LAS bf16x8*)(lds + PG8_SB(b, h) + boff + n * 2048 + k * 1024); } while (0)
; #define PG8_MMA(ai, bj, At, Bt) do { __builtin_amdgcn_s_setprio(1); _Pragma("unroll") for (int m = 0; m < 4; ++m) _Pragma("unroll") for (int n = 0; n < 2; ++n) _Pragma("unroll") for (int k = 0; k < 2; ++k) \
;         acc[ai][bj][m][n] = __builtin_amdgcn_mfma_f32_16x16x32_bf16(Bt[n][k], At[m][k], acc[ai][bj][m][n], 0, 0, 0); __builtin_amdgcn_s_setprio(0); } while (0)
; #define PG8_WAIT_V(n) asm volatile("s_waitcnt vmcnt(" #n ")" ::: "memory")
; #define PG8_WAIT_L(n) asm volatile("s_waitcnt lgkmcnt(" #n ")" ::: "memory")
; #define PG8_BAR __builtin_amdgcn_s_barrier()
; #define PG8_SCHED __builtin_amdgcn_sched_barrier(0)
; template <class Epi, class Sched, bool ALIGN_EPI = false, bool SP2 = false>
; __device__ __forceinline__ void gemm_phase(PG8_LAS unsigned char* lds, const Gemm g, const Sched& S, const Epi& E) {
;     ...
;             PG8_LDB(B0, 1, 0); PG8_LDB(B1, 1, 1); PG8_SCHED; PG8_LDA(At, 1, 0); PG8_STAGE(PG8_SA(0, 1), a2 + hstep, voffA);
;             PG8_WAIT_V(8); PG8_WAIT_L(0); PG8_BAR; PG8_MMA(0, 0, At, B0); PG8_MMA(0, 1, At, B1); PG8_BAR; PG8_SCHED;
;             PG8_LDA(At, 1, 1); PG8_STAGE(PG8_SB(1, 0), b3, voffB); PG8_STAGE(PG8_SB(1, 1), b3 + hstep, voffB); PG8_STAGE(PG8_SA(1, 0), a3, voffA);
;             PG8_WAIT_V(8); PG8_WAIT_L(0); PG8_BAR; PG8_MMA(1, 0, At, B0); PG8_MMA(1, 1, At, B1); PG8_BAR; PG8_SCHED;
	s_add_i32 s55, 0, 0x18000
	s_add_i32 s58, 0, 0x1c000
	v_add_u32_e32 v174, s55, v148
	v_add_u32_e32 v183, s58, v148
	ds_read_b128 v[162:165], v174
	ds_read_b128 v[166:169], v174 offset:1024
	ds_read_b128 v[170:173], v174 offset:2048
	ds_read_b128 v[174:177], v174 offset:3072
	ds_read_b128 v[188:191], v183
	ds_read_b128 v[196:199], v183 offset:1024
	ds_read_b128 v[200:203], v183 offset:2048
	ds_read_b128 v[204:207], v183 offset:3072
	s_add_u32 s56, s70, 0x80000
	s_addc_u32 s57, s71, 0
	s_mov_b32 m0, s39
	ds_read_b128 v[208:211], v161 offset:32768
	ds_read_b128 v[212:215], v161 offset:33792
	ds_read_b128 v[216:219], v161 offset:34816
	ds_read_b128 v[220:223], v161 offset:35840
	ds_read_b128 v[224:227], v161 offset:36864
	ds_read_b128 v[228:231], v161 offset:37888
	ds_read_b128 v[232:235], v161 offset:38912
	ds_read_b128 v[236:239], v161 offset:39936
	global_load_lds_dwordx4 v150, s[56:57]
	s_mov_b32 m0, s40
	s_nop 0
	global_load_lds_dwordx4 v154, s[56:57]
	s_waitcnt vmcnt(8)
	s_waitcnt lgkmcnt(0)
	s_barrier
	v_mfma_f32_16x16x32_bf16 v[124:127], v[162:165], v[208:211], v[124:127]
	v_mfma_f32_16x16x32_bf16 v[124:127], v[166:169], v[212:215], v[124:127]
	v_mfma_f32_16x16x32_bf16 v[116:119], v[174:177], v[212:215], v[116:119]
	v_mfma_f32_16x16x32_bf16 v[116:119], v[170:173], v[208:211], v[116:119]
	v_mfma_f32_16x16x32_bf16 v[100:103], v[170:173], v[216:219], v[100:103]
	v_mfma_f32_16x16x32_bf16 v[100:103], v[174:177], v[220:223], v[100:103]
	v_mfma_f32_16x16x32_bf16 v[108:111], v[166:169], v[220:223], v[108:111]
	v_mfma_f32_16x16x32_bf16 v[108:111], v[162:165], v[216:219], v[108:111]
	v_mfma_f32_16x16x32_bf16 v[92:95], v[162:165], v[224:227], v[92:95]
	v_mfma_f32_16x16x32_bf16 v[92:95], v[166:169], v[228:231], v[92:95]
	v_mfma_f32_16x16x32_bf16 v[84:87], v[174:177], v[228:231], v[84:87]
	v_mfma_f32_16x16x32_bf16 v[84:87], v[170:173], v[224:227], v[84:87]
	v_mfma_f32_16x16x32_bf16 v[68:71], v[170:173], v[232:235], v[68:71]
	v_mfma_f32_16x16x32_bf16 v[68:71], v[174:177], v[236:239], v[68:71]
	v_mfma_f32_16x16x32_bf16 v[76:79], v[166:169], v[236:239], v[76:79]
	v_mfma_f32_16x16x32_bf16 v[76:79], v[162:165], v[232:235], v[76:79]
	v_mfma_f32_16x16x32_bf16 v[120:123], v[188:191], v[208:211], v[120:123]
	v_mfma_f32_16x16x32_bf16 v[120:123], v[196:199], v[212:215], v[120:123]
	v_mfma_f32_16x16x32_bf16 v[112:115], v[204:207], v[212:215], v[112:115]
	v_mfma_f32_16x16x32_bf16 v[112:115], v[200:203], v[208:211], v[112:115]
	v_mfma_f32_16x16x32_bf16 v[96:99], v[200:203], v[216:219], v[96:99]
	v_mfma_f32_16x16x32_bf16 v[96:99], v[204:207], v[220:223], v[96:99]
	v_mfma_f32_16x16x32_bf16 v[104:107], v[196:199], v[220:223], v[104:107]
	v_mfma_f32_16x16x32_bf16 v[104:107], v[188:191], v[216:219], v[104:107]
	v_mfma_f32_16x16x32_bf16 v[88:91], v[188:191], v[224:227], v[88:91]
	v_mfma_f32_16x16x32_bf16 v[88:91], v[196:199], v[228:231], v[88:91]
	v_mfma_f32_16x16x32_bf16 v[80:83], v[204:207], v[228:231], v[80:83]
	v_mfma_f32_16x16x32_bf16 v[80:83], v[200:203], v[224:227], v[80:83]
	v_mfma_f32_16x16x32_bf16 v[64:67], v[200:203], v[232:235], v[64:67]
	v_mfma_f32_16x16x32_bf16 v[64:67], v[204:207], v[236:239], v[64:67]
	v_mfma_f32_16x16x32_bf16 v[72:75], v[196:199], v[236:239], v[72:75]
	v_mfma_f32_16x16x32_bf16 v[72:75], v[188:191], v[232:235], v[72:75]
	s_barrier
	s_add_i32 s55, s55, s36
	s_mov_b32 m0, s55
	ds_read_b128 v[208:211], v161 offset:49152
	ds_read_b128 v[212:215], v161 offset:50176
	ds_read_b128 v[216:219], v161 offset:51200
	ds_read_b128 v[220:223], v161 offset:52224
	ds_read_b128 v[224:227], v161 offset:53248
	ds_read_b128 v[228:231], v161 offset:54272
	ds_read_b128 v[232:235], v161 offset:55296
	ds_read_b128 v[236:239], v161 offset:56320
	global_load_lds_dwordx4 v152, s[98:99]
	s_add_i32 m0, s55, 0x2000
	s_add_u32 s56, s68, 0x80080
	s_addc_u32 s57, s69, 0
	s_add_i32 s55, s58, s36
	global_load_lds_dwordx4 v156, s[98:99]
	s_mov_b32 m0, s55
	s_nop 0
	global_load_lds_dwordx4 v152, s[56:57]
	s_add_i32 m0, s55, 0x2000
	s_nop 0
	global_load_lds_dwordx4 v156, s[56:57]
	s_mov_b32 m0, s42
	s_nop 0
	global_load_lds_dwordx4 v150, s[100:101]
	s_mov_b32 m0, s43
	s_nop 0
	global_load_lds_dwordx4 v154, s[100:101]
	s_waitcnt vmcnt(8)
	s_waitcnt lgkmcnt(0)
	s_barrier
	v_mfma_f32_16x16x32_bf16 v[60:63], v[162:165], v[208:211], v[60:63]
	v_mfma_f32_16x16x32_bf16 v[60:63], v[166:169], v[212:215], v[60:63]
	v_mfma_f32_16x16x32_bf16 v[52:55], v[174:177], v[212:215], v[52:55]
	v_mfma_f32_16x16x32_bf16 v[52:55], v[170:173], v[208:211], v[52:55]
	v_mfma_f32_16x16x32_bf16 v[36:39], v[170:173], v[216:219], v[36:39]
	v_mfma_f32_16x16x32_bf16 v[36:39], v[174:177], v[220:223], v[36:39]
	v_mfma_f32_16x16x32_bf16 v[44:47], v[166:169], v[220:223], v[44:47]
	v_mfma_f32_16x16x32_bf16 v[44:47], v[162:165], v[216:219], v[44:47]
	v_mfma_f32_16x16x32_bf16 v[28:31], v[162:165], v[224:227], v[28:31]
	v_mfma_f32_16x16x32_bf16 v[28:31], v[166:169], v[228:231], v[28:31]
	v_mfma_f32_16x16x32_bf16 v[20:23], v[174:177], v[228:231], v[20:23]
	v_mfma_f32_16x16x32_bf16 v[20:23], v[170:173], v[224:227], v[20:23]
	v_mfma_f32_16x16x32_bf16 v[4:7], v[170:173], v[232:235], v[4:7]
	v_mfma_f32_16x16x32_bf16 v[4:7], v[174:177], v[236:239], v[4:7]
	v_mfma_f32_16x16x32_bf16 v[12:15], v[166:169], v[236:239], v[12:15]
	v_mfma_f32_16x16x32_bf16 v[12:15], v[162:165], v[232:235], v[12:15]
	v_mfma_f32_16x16x32_bf16 v[56:59], v[188:191], v[208:211], v[56:59]
	v_mfma_f32_16x16x32_bf16 v[56:59], v[196:199], v[212:215], v[56:59]
	v_mfma_f32_16x16x32_bf16 v[48:51], v[204:207], v[212:215], v[48:51]
	v_mfma_f32_16x16x32_bf16 v[48:51], v[200:203], v[208:211], v[48:51]
	v_mfma_f32_16x16x32_bf16 v[32:35], v[200:203], v[216:219], v[32:35]
	v_mfma_f32_16x16x32_bf16 v[32:35], v[204:207], v[220:223], v[32:35]
	v_mfma_f32_16x16x32_bf16 v[40:43], v[196:199], v[220:223], v[40:43]
	v_mfma_f32_16x16x32_bf16 v[40:43], v[188:191], v[216:219], v[40:43]
	v_mfma_f32_16x16x32_bf16 v[24:27], v[188:191], v[224:227], v[24:27]
	v_mfma_f32_16x16x32_bf16 v[24:27], v[196:199], v[228:231], v[24:27]
	v_mfma_f32_16x16x32_bf16 v[16:19], v[204:207], v[228:231], v[16:19]
	v_mfma_f32_16x16x32_bf16 v[16:19], v[200:203], v[224:227], v[16:19]
	v_mfma_f32_16x16x32_bf16 v[0:3], v[200:203], v[232:235], v[0:3]
	v_mfma_f32_16x16x32_bf16 v[0:3], v[204:207], v[236:239], v[0:3]
	v_mfma_f32_16x16x32_bf16 v[8:11], v[196:199], v[236:239], v[8:11]
	v_mfma_f32_16x16x32_bf16 v[8:11], v[188:191], v[232:235], v[8:11]
	s_barrier
	s_add_i32 s54, s54, 2
	s_add_u32 s66, s66, 0x100
	s_addc_u32 s67, s67, 0
	s_add_u32 s52, s52, 0x100
	s_addc_u32 s53, s53, 0
	s_cmp_gt_u32 s54, 29
	s_cbranch_scc0 .LBB0_192
	s_setprio 0
	s_and_b64 vcc, exec, s[14:15]
	s_cbranch_vccz .LBB0_195
	s_barrier

;     __device__ __forceinline__ bool next(int i, Unit& u) const { if (i > 0 || c >= nitems) return false; u.pm = 64; u.pn = c % npn; u.k0 = (c / npn) * kslice; return true; }
; #define PG8_STAGE(bufoff, gbase, voff) do { _Pragma("unroll") for (int _i = 0; _i < 2; ++_i) \
;         __builtin_amdgcn_global_load_lds((const unsigned*)((const char*)(gbase) + (voff)[_i]), (PG8_LAS unsigned*)(lds + (bufoff) + ldsw + _i * 8192), 16, 0, 0); } while (0)
; #define PG8_LDA(dst, b, h) do { _Pragma("unroll") for (int m = 0; m < 4; ++m) _Pragma("unroll") for (int k = 0; k < 2; ++k) dst[m][k] = *(const PG8_LAS bf16x8*)(lds + PG8_SA(b, h) + aoff + m * 2048 + k * 1024); } while (0)
; #define PG8_LDB(dst, b, h) do { _Pragma("unroll") for (int n = 0; n < 2; ++n) _Pragma("unroll") for (int k = 0; k < 2; ++k) dst[n][k] = *(const PG8_LAS bf16x8*)(lds + PG8_SB(b, h) + boff + n * 2048 + k * 1024); } while (0)
; #define PG8_WAIT_V(n) asm volatile("s_waitcnt vmcnt(" #n ")" ::: "memory")
; template <class Epi, class Sched, bool ALIGN_EPI = false, bool SP2 = false>
; __device__ __forceinline__ void gemm_phase(PG8_LAS unsigned char* lds, const Gemm g, const Sched& S, const Epi& E) {
;     ...
;         const bool has_next = S.next(ui + 1, nxt);
;         const char* nA = has_next ? (const char*)g.A + (size_t)nxt.pm * tstep + (size_t)nxt.k0 * 2 : cA; const char* nB = has_next ? (const char*)g.Bt + (size_t)nxt.pn * tstep + (size_t)nxt.k0 * 2 : cB;
;         for (int t = 0; t < nt; t += 2) {
;             const bool last = (t == nt - 2);
;             const char* a1 = cA + (size_t)(t + 1) * kstep;
;             const char* a2 = last ? nA : cA + (size_t)(t + 2) * kstep; const char* b2 = last ? nB : cB + (size_t)(t + 2) * kstep;
;             const char* a3 = a2 + kstep; const char* b3 = b2 + kstep;
;             if (last && has_next) S.a_ready(nxt);
;             if constexpr (SP2) {
;             PG8_LDB(B0, 0, 0); PG8_LDB(B1, 0, 1); PG8_SCHED; PG8_LDA(At, 0, 0); PG8_STAGE(PG8_SA(1, 1), a1 + hstep, voffA);
;             PG8_WAIT_V(8); PG8_WAIT_L(0); PG8_BAR; PG8_MMA(0, 0, At, B0); PG8_MMA(0, 1, At, B1); PG8_BAR; PG8_SCHED;
;             PG8_LDA(At, 0, 1); PG8_STAGE(PG8_SB(0, 0), b2, voffB); PG8_STAGE(PG8_SB(0, 1), b2 + hstep, voffB); PG8_STAGE(PG8_SA(0, 0), a2, voffA);
;             PG8_WAIT_V(8); PG8_WAIT_L(0); PG8_BAR; PG8_MMA(1, 0, At, B0); PG8_MMA(1, 1, At, B1); PG8_BAR; PG8_SCHED;
.Lsp_skip_5:
.LBB0_308:
	ds_read_b128 v[128:131], v155
	ds_read_b128 v[132:135], v155 offset:1024
	ds_read_b128 v[170:173], v155 offset:2048
	ds_read_b128 v[174:177], v155 offset:3072
	ds_read_b128 v[196:199], v157
	ds_read_b128 v[200:203], v157 offset:1024
	ds_read_b128 v[204:207], v157 offset:2048
	ds_read_b128 v[208:211], v157 offset:3072
	s_add_u32 s12, s10, 0xffea0080
	s_addc_u32 s13, s11, -1
	s_cmpk_eq_i32 s40, 0x54
	s_cselect_b32 s15, s77, s13
	s_cselect_b32 s14, s76, s12
	s_cselect_b32 s13, s79, s39
	s_cselect_b32 s12, s78, s17
	s_add_i32 m0, s54, 0xc000
	ds_read_b128 v[212:215], v161
	ds_read_b128 v[216:219], v161 offset:1024
	ds_read_b128 v[220:223], v161 offset:2048
	ds_read_b128 v[224:227], v161 offset:3072
	ds_read_b128 v[228:231], v161 offset:4096
	ds_read_b128 v[232:235], v161 offset:5120
	ds_read_b128 v[236:239], v161 offset:6144
	ds_read_b128 v[240:243], v161 offset:7168
	global_load_lds_dwordx4 v162, s[10:11]
	s_add_i32 m0, s54, 0xe000
	s_nop 0
	global_load_lds_dwordx4 v164, s[10:11]
	s_waitcnt vmcnt(8)
	s_waitcnt lgkmcnt(0)
	s_barrier
	v_mfma_f32_16x16x32_bf16 v[124:127], v[128:131], v[212:215], v[124:127]
	v_mfma_f32_16x16x32_bf16 v[124:127], v[132:135], v[216:219], v[124:127]
	v_mfma_f32_16x16x32_bf16 v[120:123], v[174:177], v[216:219], v[120:123]
	v_mfma_f32_16x16x32_bf16 v[120:123], v[170:173], v[212:215], v[120:123]
	v_mfma_f32_16x16x32_bf16 v[104:107], v[170:173], v[220:223], v[104:107]
	v_mfma_f32_16x16x32_bf16 v[104:107], v[174:177], v[224:227], v[104:107]
	v_mfma_f32_16x16x32_bf16 v[108:111], v[132:135], v[224:227], v[108:111]
	v_mfma_f32_16x16x32_bf16 v[108:111], v[128:131], v[220:223], v[108:111]
	v_mfma_f32_16x16x32_bf16 v[92:95], v[128:131], v[228:231], v[92:95]
	v_mfma_f32_16x16x32_bf16 v[92:95], v[132:135], v[232:235], v[92:95]
	v_mfma_f32_16x16x32_bf16 v[88:91], v[174:177], v[232:235], v[88:91]
	v_mfma_f32_16x16x32_bf16 v[88:91], v[170:173], v[228:231], v[88:91]
	v_mfma_f32_16x16x32_bf16 v[72:75], v[170:173], v[236:239], v[72:75]
	v_mfma_f32_16x16x32_bf16 v[72:75], v[174:177], v[240:243], v[72:75]
	v_mfma_f32_16x16x32_bf16 v[76:79], v[132:135], v[240:243], v[76:79]
	v_mfma_f32_16x16x32_bf16 v[76:79], v[128:131], v[236:239], v[76:79]
	v_mfma_f32_16x16x32_bf16 v[116:119], v[196:199], v[212:215], v[116:119]
	v_mfma_f32_16x16x32_bf16 v[116:119], v[200:203], v[216:219], v[116:119]
	v_mfma_f32_16x16x32_bf16 v[112:115], v[208:211], v[216:219], v[112:115]
	v_mfma_f32_16x16x32_bf16 v[112:115], v[204:207], v[212:215], v[112:115]
	v_mfma_f32_16x16x32_bf16 v[96:99], v[204:207], v[220:223], v[96:99]
	v_mfma_f32_16x16x32_bf16 v[96:99], v[208:211], v[224:227], v[96:99]
	v_mfma_f32_16x16x32_bf16 v[100:103], v[200:203], v[224:227], v[100:103]
	v_mfma_f32_16x16x32_bf16 v[100:103], v[196:199], v[220:223], v[100:103]
	v_mfma_f32_16x16x32_bf16 v[84:87], v[196:199], v[228:231], v[84:87]
	v_mfma_f32_16x16x32_bf16 v[84:87], v[200:203], v[232:235], v[84:87]
	v_mfma_f32_16x16x32_bf16 v[80:83], v[208:211], v[232:235], v[80:83]
	v_mfma_f32_16x16x32_bf16 v[80:83], v[204:207], v[228:231], v[80:83]
	v_mfma_f32_16x16x32_bf16 v[64:67], v[204:207], v[236:239], v[64:67]
	v_mfma_f32_16x16x32_bf16 v[64:67], v[208:211], v[240:243], v[64:67]
	v_mfma_f32_16x16x32_bf16 v[68:71], v[200:203], v[240:243], v[68:71]
	v_mfma_f32_16x16x32_bf16 v[68:71], v[196:199], v[236:239], v[68:71]
	s_barrier
	s_add_u32 s98, s12, 0x80
	s_addc_u32 s99, s13, 0
	s_add_u32 s100, s14, 0x80
	s_addc_u32 s101, s15, 0
	s_add_i32 s41, s92, s53
	s_mov_b32 m0, s41
	ds_read_b128 v[212:215], v161 offset:16384
	ds_read_b128 v[216:219], v161 offset:17408
	ds_read_b128 v[220:223], v161 offset:18432
	ds_read_b128 v[224:227], v161 offset:19456
	ds_read_b128 v[228:231], v161 offset:20480
	ds_read_b128 v[232:235], v161 offset:21504
	ds_read_b128 v[236:239], v161 offset:22528
	ds_read_b128 v[240:243], v161 offset:23552
	global_load_lds_dwordx4 v144, s[12:13]
	s_add_i32 m0, s41, 0x2000
	s_add_u32 s42, s12, 0x160000
	s_addc_u32 s43, s13, 0
	s_add_i32 s41, s93, s53
	global_load_lds_dwordx4 v148, s[12:13]
	s_mov_b32 m0, s41
	s_nop 0
	global_load_lds_dwordx4 v144, s[42:43]
	s_add_i32 m0, s41, 0x2000
	s_nop 0
	global_load_lds_dwordx4 v148, s[42:43]
	s_mov_b32 m0, s54
	s_nop 0
	global_load_lds_dwordx4 v142, s[14:15]
	s_mov_b32 m0, s55
	s_nop 0
	global_load_lds_dwordx4 v146, s[14:15]
	s_waitcnt vmcnt(8)
	s_waitcnt lgkmcnt(0)
	s_barrier
	v_mfma_f32_16x16x32_bf16 v[60:63], v[128:131], v[212:215], v[60:63]
	v_mfma_f32_16x16x32_bf16 v[60:63], v[132:135], v[216:219], v[60:63]
	v_mfma_f32_16x16x32_bf16 v[56:59], v[174:177], v[216:219], v[56:59]
	v_mfma_f32_16x16x32_bf16 v[56:59], v[170:173], v[212:215], v[56:59]
	v_mfma_f32_16x16x32_bf16 v[40:43], v[170:173], v[220:223], v[40:43]
	v_mfma_f32_16x16x32_bf16 v[40:43], v[174:177], v[224:227], v[40:43]
	v_mfma_f32_16x16x32_bf16 v[44:47], v[132:135], v[224:227], v[44:47]
	v_mfma_f32_16x16x32_bf16 v[44:47], v[128:131], v[220:223], v[44:47]
	v_mfma_f32_16x16x32_bf16 v[28:31], v[128:131], v[228:231], v[28:31]
	v_mfma_f32_16x16x32_bf16 v[28:31], v[132:135], v[232:235], v[28:31]
	v_mfma_f32_16x16x32_bf16 v[24:27], v[174:177], v[232:235], v[24:27]
	v_mfma_f32_16x16x32_bf16 v[24:27], v[170:173], v[228:231], v[24:27]
	v_mfma_f32_16x16x32_bf16 v[8:11], v[170:173], v[236:239], v[8:11]
	v_mfma_f32_16x16x32_bf16 v[8:11], v[174:177], v[240:243], v[8:11]
	v_mfma_f32_16x16x32_bf16 v[12:15], v[132:135], v[240:243], v[12:15]
	v_mfma_f32_16x16x32_bf16 v[12:15], v[128:131], v[236:239], v[12:15]
	v_mfma_f32_16x16x32_bf16 v[52:55], v[196:199], v[212:215], v[52:55]
	v_mfma_f32_16x16x32_bf16 v[52:55], v[200:203], v[216:219], v[52:55]
	v_mfma_f32_16x16x32_bf16 v[48:51], v[208:211], v[216:219], v[48:51]
	v_mfma_f32_16x16x32_bf16 v[48:51], v[204:207], v[212:215], v[48:51]
	v_mfma_f32_16x16x32_bf16 v[32:35], v[204:207], v[220:223], v[32:35]
	v_mfma_f32_16x16x32_bf16 v[32:35], v[208:211], v[224:227], v[32:35]
	v_mfma_f32_16x16x32_bf16 v[36:39], v[200:203], v[224:227], v[36:39]
	v_mfma_f32_16x16x32_bf16 v[36:39], v[196:199], v[220:223], v[36:39]
	v_mfma_f32_16x16x32_bf16 v[20:23], v[196:199], v[228:231], v[20:23]
	v_mfma_f32_16x16x32_bf16 v[20:23], v[200:203], v[232:235], v[20:23]
	v_mfma_f32_16x16x32_bf16 v[16:19], v[208:211], v[232:235], v[16:19]
	v_mfma_f32_16x16x32_bf16 v[16:19], v[204:207], v[228:231], v[16:19]
	v_mfma_f32_16x16x32_bf16 v[0:3], v[204:207], v[236:239], v[0:3]
	v_mfma_f32_16x16x32_bf16 v[0:3], v[208:211], v[240:243], v[0:3]
	v_mfma_f32_16x16x32_bf16 v[4:7], v[200:203], v[240:243], v[4:7]
	v_mfma_f32_16x16x32_bf16 v[4:7], v[196:199], v[236:239], v[4:7]
	s_barrier
; #define PG8_STAGE(bufoff, gbase, voff) do { _Pragma("unroll") for (int _i = 0; _i < 2; ++_i) \
;         __builtin_amdgcn_global_load_lds((const unsigned*)((const char*)(gbase) + (voff)[_i]), (PG8_LAS unsigned*)(lds + (bufoff) + ldsw + _i * 8192), 16, 0, 0); } while (0)
; #define PG8_LDA(dst, b, h) do { _Pragma("unroll") for (int m = 0; m < 4; ++m) _Pragma("unroll") for (int k = 0; k < 2; ++k) dst[m][k] = *(const PG8_LAS bf16x8*)(lds + PG8_SA(b, h) + aoff + m * 2048 + k * 1024); } while (0)
; #define PG8_LDB(dst, b, h) do { _Pragma("unroll") for (int n = 0; n < 2; ++n) _Pragma("unroll") for (int k = 0; k < 2; ++k) dst[n][k] = *(const PG8_LAS bf16x8*)(lds + PG8_SB(b, h) + boff + n * 2048 + k * 1024); } while (0)
; #define PG8_MMA(ai, bj, At, Bt) do { __builtin_amdgcn_s_setprio(1); _Pragma("unroll") for (int m = 0; m < 4; ++m) _Pragma("unroll") for (int n = 0; n < 2; ++n) _Pragma("unroll") for (int k = 0; k < 2; ++k) \
;         acc[ai][bj][m][n] = __builtin_amdgcn_mfma_f32_16x16x32_bf16(Bt[n][k], At[m][k], acc[ai][bj][m][n], 0, 0, 0); __builtin_amdgcn_s_setprio(0); } while (0)
; #define PG8_WAIT_V(n) asm volatile("s_waitcnt vmcnt(" #n ")" ::: "memory")
; #define PG8_WAIT_L(n) asm volatile("s_waitcnt lgkmcnt(" #n ")" ::: "memory")
; #define PG8_BAR __builtin_amdgcn_s_barrier()
; #define PG8_SCHED __builtin_amdgcn_sched_barrier(0)
; template <class Epi, class Sched, bool ALIGN_EPI = false, bool SP2 = false>
; __device__ __forceinline__ void gemm_phase(PG8_LAS unsigned char* lds, const Gemm g, const Sched& S, const Epi& E) {
;     ...
;             PG8_LDB(B0, 1, 0); PG8_LDB(B1, 1, 1); PG8_SCHED; PG8_LDA(At, 1, 0); PG8_STAGE(PG8_SA(0, 1), a2 + hstep, voffA);
;             PG8_WAIT_V(8); PG8_WAIT_L(0); PG8_BAR; PG8_MMA(0, 0, At, B0); PG8_MMA(0, 1, At, B1); PG8_BAR; PG8_SCHED;
;             PG8_LDA(At, 1, 1); PG8_STAGE(PG8_SB(1, 0), b3, voffB); PG8_STAGE(PG8_SB(1, 1), b3 + hstep, voffB); PG8_STAGE(PG8_SA(1, 0), a3, voffA);
;             PG8_WAIT_V(8); PG8_WAIT_L(0); PG8_BAR; PG8_MMA(1, 0, At, B0); PG8_MMA(1, 1, At, B1); PG8_BAR; PG8_SCHED;
	s_add_i32 s41, 0, 0x18000
	v_add_u32_e32 v158, s41, v151
	s_add_i32 s42, 0, 0x1c000
	ds_read_b128 v[128:131], v158
	ds_read_b128 v[132:135], v158 offset:1024
	ds_read_b128 v[170:173], v158 offset:2048
	ds_read_b128 v[174:177], v158 offset:3072
	v_add_u32_e32 v158, s42, v151
	ds_read_b128 v[196:199], v158
	ds_read_b128 v[200:203], v158 offset:1024
	ds_read_b128 v[204:207], v158 offset:2048
	ds_read_b128 v[208:211], v158 offset:3072
	s_add_u32 s14, s14, 0x160000
	s_addc_u32 s15, s15, 0
	s_mov_b32 m0, s56
	ds_read_b128 v[212:215], v161 offset:32768
	ds_read_b128 v[216:219], v161 offset:33792
	ds_read_b128 v[220:223], v161 offset:34816
	ds_read_b128 v[224:227], v161 offset:35840
	ds_read_b128 v[228:231], v161 offset:36864
	ds_read_b128 v[232:235], v161 offset:37888
	ds_read_b128 v[236:239], v161 offset:38912
	ds_read_b128 v[240:243], v161 offset:39936
	global_load_lds_dwordx4 v142, s[14:15]
	s_mov_b32 m0, s57
	s_nop 0
	global_load_lds_dwordx4 v146, s[14:15]
	s_waitcnt vmcnt(8)
	s_waitcnt lgkmcnt(0)
	s_barrier
	v_mfma_f32_16x16x32_bf16 v[124:127], v[128:131], v[212:215], v[124:127]
	v_mfma_f32_16x16x32_bf16 v[124:127], v[132:135], v[216:219], v[124:127]
	v_mfma_f32_16x16x32_bf16 v[120:123], v[174:177], v[216:219], v[120:123]
	v_mfma_f32_16x16x32_bf16 v[120:123], v[170:173], v[212:215], v[120:123]
	v_mfma_f32_16x16x32_bf16 v[104:107], v[170:173], v[220:223], v[104:107]
	v_mfma_f32_16x16x32_bf16 v[104:107], v[174:177], v[224:227], v[104:107]
	v_mfma_f32_16x16x32_bf16 v[108:111], v[132:135], v[224:227], v[108:111]
	v_mfma_f32_16x16x32_bf16 v[108:111], v[128:131], v[220:223], v[108:111]
	v_mfma_f32_16x16x32_bf16 v[92:95], v[128:131], v[228:231], v[92:95]
	v_mfma_f32_16x16x32_bf16 v[92:95], v[132:135], v[232:235], v[92:95]
	v_mfma_f32_16x16x32_bf16 v[88:91], v[174:177], v[232:235], v[88:91]
	v_mfma_f32_16x16x32_bf16 v[88:91], v[170:173], v[228:231], v[88:91]
	v_mfma_f32_16x16x32_bf16 v[72:75], v[170:173], v[236:239], v[72:75]
	v_mfma_f32_16x16x32_bf16 v[72:75], v[174:177], v[240:243], v[72:75]
	v_mfma_f32_16x16x32_bf16 v[76:79], v[132:135], v[240:243], v[76:79]
	v_mfma_f32_16x16x32_bf16 v[76:79], v[128:131], v[236:239], v[76:79]
	v_mfma_f32_16x16x32_bf16 v[116:119], v[196:199], v[212:215], v[116:119]
	v_mfma_f32_16x16x32_bf16 v[116:119], v[200:203], v[216:219], v[116:119]
	v_mfma_f32_16x16x32_bf16 v[112:115], v[208:211], v[216:219], v[112:115]
	v_mfma_f32_16x16x32_bf16 v[112:115], v[204:207], v[212:215], v[112:115]
	v_mfma_f32_16x16x32_bf16 v[96:99], v[204:207], v[220:223], v[96:99]
	v_mfma_f32_16x16x32_bf16 v[96:99], v[208:211], v[224:227], v[96:99]
	v_mfma_f32_16x16x32_bf16 v[100:103], v[200:203], v[224:227], v[100:103]
	v_mfma_f32_16x16x32_bf16 v[100:103], v[196:199], v[220:223], v[100:103]
	v_mfma_f32_16x16x32_bf16 v[84:87], v[196:199], v[228:231], v[84:87]
	v_mfma_f32_16x16x32_bf16 v[84:87], v[200:203], v[232:235], v[84:87]
	v_mfma_f32_16x16x32_bf16 v[80:83], v[208:211], v[232:235], v[80:83]
	v_mfma_f32_16x16x32_bf16 v[80:83], v[204:207], v[228:231], v[80:83]
	v_mfma_f32_16x16x32_bf16 v[64:67], v[204:207], v[236:239], v[64:67]
	v_mfma_f32_16x16x32_bf16 v[64:67], v[208:211], v[240:243], v[64:67]
	v_mfma_f32_16x16x32_bf16 v[68:71], v[200:203], v[240:243], v[68:71]
	v_mfma_f32_16x16x32_bf16 v[68:71], v[196:199], v[236:239], v[68:71]
	s_barrier
	s_add_i32 s14, s41, s53
	s_mov_b32 m0, s14
	ds_read_b128 v[212:215], v161 offset:49152
	ds_read_b128 v[216:219], v161 offset:50176
	ds_read_b128 v[220:223], v161 offset:51200
	ds_read_b128 v[224:227], v161 offset:52224
	ds_read_b128 v[228:231], v161 offset:53248
	ds_read_b128 v[232:235], v161 offset:54272
	ds_read_b128 v[236:239], v161 offset:55296
	ds_read_b128 v[240:243], v161 offset:56320
	global_load_lds_dwordx4 v144, s[98:99]
	s_add_i32 m0, s14, 0x2000
	s_add_u32 s12, s12, 0x160080
	s_addc_u32 s13, s13, 0
	s_add_i32 s14, s42, s53
	global_load_lds_dwordx4 v148, s[98:99]
	s_mov_b32 m0, s14
	s_nop 0
	global_load_lds_dwordx4 v144, s[12:13]
	s_add_i32 m0, s14, 0x2000
	s_nop 0
	global_load_lds_dwordx4 v148, s[12:13]
	s_mov_b32 m0, s84
	s_nop 0
	global_load_lds_dwordx4 v142, s[100:101]
	s_mov_b32 m0, s85
	s_nop 0
	global_load_lds_dwordx4 v146, s[100:101]
	s_waitcnt vmcnt(8)
	s_waitcnt lgkmcnt(0)
	s_barrier
	v_mfma_f32_16x16x32_bf16 v[60:63], v[128:131], v[212:215], v[60:63]
	v_mfma_f32_16x16x32_bf16 v[60:63], v[132:135], v[216:219], v[60:63]
	v_mfma_f32_16x16x32_bf16 v[56:59], v[174:177], v[216:219], v[56:59]
	v_mfma_f32_16x16x32_bf16 v[56:59], v[170:173], v[212:215], v[56:59]
	v_mfma_f32_16x16x32_bf16 v[40:43], v[170:173], v[220:223], v[40:43]
	v_mfma_f32_16x16x32_bf16 v[40:43], v[174:177], v[224:227], v[40:43]
	v_mfma_f32_16x16x32_bf16 v[44:47], v[132:135], v[224:227], v[44:47]
	v_mfma_f32_16x16x32_bf16 v[44:47], v[128:131], v[220:223], v[44:47]
	v_mfma_f32_16x16x32_bf16 v[28:31], v[128:131], v[228:231], v[28:31]
	v_mfma_f32_16x16x32_bf16 v[28:31], v[132:135], v[232:235], v[28:31]
	v_mfma_f32_16x16x32_bf16 v[24:27], v[174:177], v[232:235], v[24:27]
	v_mfma_f32_16x16x32_bf16 v[24:27], v[170:173], v[228:231], v[24:27]
	v_mfma_f32_16x16x32_bf16 v[8:11], v[170:173], v[236:239], v[8:11]
	v_mfma_f32_16x16x32_bf16 v[8:11], v[174:177], v[240:243], v[8:11]
	v_mfma_f32_16x16x32_bf16 v[12:15], v[132:135], v[240:243], v[12:15]
	v_mfma_f32_16x16x32_bf16 v[12:15], v[128:131], v[236:239], v[12:15]
	v_mfma_f32_16x16x32_bf16 v[52:55], v[196:199], v[212:215], v[52:55]
	v_mfma_f32_16x16x32_bf16 v[52:55], v[200:203], v[216:219], v[52:55]
	v_mfma_f32_16x16x32_bf16 v[48:51], v[208:211], v[216:219], v[48:51]
	v_mfma_f32_16x16x32_bf16 v[48:51], v[204:207], v[212:215], v[48:51]
	v_mfma_f32_16x16x32_bf16 v[32:35], v[204:207], v[220:223], v[32:35]
	v_mfma_f32_16x16x32_bf16 v[32:35], v[208:211], v[224:227], v[32:35]
	v_mfma_f32_16x16x32_bf16 v[36:39], v[200:203], v[224:227], v[36:39]
	v_mfma_f32_16x16x32_bf16 v[36:39], v[196:199], v[220:223], v[36:39]
	v_mfma_f32_16x16x32_bf16 v[20:23], v[196:199], v[228:231], v[20:23]
	v_mfma_f32_16x16x32_bf16 v[20:23], v[200:203], v[232:235], v[20:23]
	v_mfma_f32_16x16x32_bf16 v[16:19], v[208:211], v[232:235], v[16:19]
	v_mfma_f32_16x16x32_bf16 v[16:19], v[204:207], v[228:231], v[16:19]
	v_mfma_f32_16x16x32_bf16 v[0:3], v[204:207], v[236:239], v[0:3]
	v_mfma_f32_16x16x32_bf16 v[0:3], v[208:211], v[240:243], v[0:3]
	v_mfma_f32_16x16x32_bf16 v[4:7], v[200:203], v[240:243], v[4:7]
	v_mfma_f32_16x16x32_bf16 v[4:7], v[196:199], v[236:239], v[4:7]
	s_barrier
	s_add_i32 s40, s40, 2
	s_add_u32 s10, s10, 0x100
	s_addc_u32 s11, s11, 0
	s_add_u32 s17, s17, 0x100
	s_addc_u32 s39, s39, 0
	s_cmpk_gt_u32 s40, 0x55
	s_cbranch_scc0 .LBB0_308
	s_setprio 0
	s_and_b64 vcc, exec, s[74:75]
	s_cbranch_vccz .LBB0_311
	s_barrier

;     __device__ __forceinline__ bool next(int i, Unit& u) const { if (i > 0 || c >= nitems) return false; u.pm = 64; u.pn = c % npn; u.k0 = (c / npn) * kslice; return true; }
; #define PG8_STAGE(bufoff, gbase, voff) do { _Pragma("unroll") for (int _i = 0; _i < 2; ++_i) \
;         __builtin_amdgcn_global_load_lds((const unsigned*)((const char*)(gbase) + (voff)[_i]), (PG8_LAS unsigned*)(lds + (bufoff) + ldsw + _i * 8192), 16, 0, 0); } while (0)
; #define PG8_LDA(dst, b, h) do { _Pragma("unroll") for (int m = 0; m < 4; ++m) _Pragma("unroll") for (int k = 0; k < 2; ++k) dst[m][k] = *(const PG8_LAS bf16x8*)(lds + PG8_SA(b, h) + aoff + m * 2048 + k * 1024); } while (0)
; #define PG8_LDB(dst, b, h) do { _Pragma("unroll") for (int n = 0; n < 2; ++n) _Pragma("unroll") for (int k = 0; k < 2; ++k) dst[n][k] = *(const PG8_LAS bf16x8*)(lds + PG8_SB(b, h) + boff + n * 2048 + k * 1024); } while (0)
; #define PG8_WAIT_V(n) asm volatile("s_waitcnt vmcnt(" #n ")" ::: "memory")
; template <class Epi, class Sched, bool ALIGN_EPI = false, bool SP2 = false>
; __device__ __forceinline__ void gemm_phase(PG8_LAS unsigned char* lds, const Gemm g, const Sched& S, const Epi& E) {
;     ...
;         const bool has_next = S.next(ui + 1, nxt);
;         const char* nA = has_next ? (const char*)g.A + (size_t)nxt.pm * tstep + (size_t)nxt.k0 * 2 : cA; const char* nB = has_next ? (const char*)g.Bt + (size_t)nxt.pn * tstep + (size_t)nxt.k0 * 2 : cB;
;         for (int t = 0; t < nt; t += 2) {
;             const bool last = (t == nt - 2);
;             const char* a1 = cA + (size_t)(t + 1) * kstep;
;             const char* a2 = last ? nA : cA + (size_t)(t + 2) * kstep; const char* b2 = last ? nB : cB + (size_t)(t + 2) * kstep;
;             const char* a3 = a2 + kstep; const char* b3 = b2 + kstep;
;             if (last && has_next) S.a_ready(nxt);
;             if constexpr (SP2) {
;             PG8_LDB(B0, 0, 0); PG8_LDB(B1, 0, 1); PG8_SCHED; PG8_LDA(At, 0, 0); PG8_STAGE(PG8_SA(1, 1), a1 + hstep, voffA);
;             PG8_WAIT_V(8); PG8_WAIT_L(0); PG8_BAR; PG8_MMA(0, 0, At, B0); PG8_MMA(0, 1, At, B1); PG8_BAR; PG8_SCHED;
;             PG8_LDA(At, 0, 1); PG8_STAGE(PG8_SB(0, 0), b2, voffB); PG8_STAGE(PG8_SB(0, 1), b2 + hstep, voffB); PG8_STAGE(PG8_SA(0, 0), a2, voffA);
;             PG8_WAIT_V(8); PG8_WAIT_L(0); PG8_BAR; PG8_MMA(1, 0, At, B0); PG8_MMA(1, 1, At, B1); PG8_BAR; PG8_SCHED;
.Lsp_skip_4:
.LBB0_623:
	ds_read_b128 v[162:165], v147
	ds_read_b128 v[166:169], v147 offset:1024
	ds_read_b128 v[172:175], v147 offset:2048
	ds_read_b128 v[196:199], v147 offset:3072
	ds_read_b128 v[200:203], v149
	ds_read_b128 v[204:207], v149 offset:1024
	ds_read_b128 v[208:211], v149 offset:2048
	ds_read_b128 v[212:215], v149 offset:3072
	s_add_u32 s43, s10, 0xfff80080
	s_addc_u32 s44, s11, -1
	s_cmp_eq_u32 s42, 28
	s_cselect_b32 s79, s36, s44
	s_cselect_b32 s78, s37, s43
	s_cselect_b32 s77, s38, s41
	s_cselect_b32 s76, s39, s40
	s_add_i32 m0, s86, 0xc000
	ds_read_b128 v[216:219], v159
	ds_read_b128 v[220:223], v159 offset:1024
	ds_read_b128 v[224:227], v159 offset:2048
	ds_read_b128 v[228:231], v159 offset:3072
	ds_read_b128 v[232:235], v159 offset:4096
	ds_read_b128 v[236:239], v159 offset:5120
	ds_read_b128 v[240:243], v159 offset:6144
	ds_read_b128 v[244:247], v159 offset:7168
	global_load_lds_dwordx4 v132, s[10:11]
	s_add_i32 m0, s86, 0xe000
	s_nop 0
	global_load_lds_dwordx4 v134, s[10:11]
	s_waitcnt vmcnt(8)
	s_waitcnt lgkmcnt(0)
	s_barrier
	v_mfma_f32_16x16x32_bf16 v[124:127], v[162:165], v[216:219], v[124:127]
	v_mfma_f32_16x16x32_bf16 v[124:127], v[166:169], v[220:223], v[124:127]
	v_mfma_f32_16x16x32_bf16 v[120:123], v[196:199], v[220:223], v[120:123]
	v_mfma_f32_16x16x32_bf16 v[120:123], v[172:175], v[216:219], v[120:123]
	v_mfma_f32_16x16x32_bf16 v[104:107], v[172:175], v[224:227], v[104:107]
	v_mfma_f32_16x16x32_bf16 v[104:107], v[196:199], v[228:231], v[104:107]
	v_mfma_f32_16x16x32_bf16 v[108:111], v[166:169], v[228:231], v[108:111]
	v_mfma_f32_16x16x32_bf16 v[108:111], v[162:165], v[224:227], v[108:111]
	v_mfma_f32_16x16x32_bf16 v[92:95], v[162:165], v[232:235], v[92:95]
	v_mfma_f32_16x16x32_bf16 v[92:95], v[166:169], v[236:239], v[92:95]
	v_mfma_f32_16x16x32_bf16 v[88:91], v[196:199], v[236:239], v[88:91]
	v_mfma_f32_16x16x32_bf16 v[88:91], v[172:175], v[232:235], v[88:91]
	v_mfma_f32_16x16x32_bf16 v[72:75], v[172:175], v[240:243], v[72:75]
	v_mfma_f32_16x16x32_bf16 v[72:75], v[196:199], v[244:247], v[72:75]
	v_mfma_f32_16x16x32_bf16 v[76:79], v[166:169], v[244:247], v[76:79]
	v_mfma_f32_16x16x32_bf16 v[76:79], v[162:165], v[240:243], v[76:79]
	v_mfma_f32_16x16x32_bf16 v[116:119], v[200:203], v[216:219], v[116:119]
	v_mfma_f32_16x16x32_bf16 v[116:119], v[204:207], v[220:223], v[116:119]
	v_mfma_f32_16x16x32_bf16 v[112:115], v[212:215], v[220:223], v[112:115]
	v_mfma_f32_16x16x32_bf16 v[112:115], v[208:211], v[216:219], v[112:115]
	v_mfma_f32_16x16x32_bf16 v[96:99], v[208:211], v[224:227], v[96:99]
	v_mfma_f32_16x16x32_bf16 v[96:99], v[212:215], v[228:231], v[96:99]
	v_mfma_f32_16x16x32_bf16 v[100:103], v[204:207], v[228:231], v[100:103]
	v_mfma_f32_16x16x32_bf16 v[100:103], v[200:203], v[224:227], v[100:103]
	v_mfma_f32_16x16x32_bf16 v[84:87], v[200:203], v[232:235], v[84:87]
	v_mfma_f32_16x16x32_bf16 v[84:87], v[204:207], v[236:239], v[84:87]
	v_mfma_f32_16x16x32_bf16 v[80:83], v[212:215], v[236:239], v[80:83]
	v_mfma_f32_16x16x32_bf16 v[80:83], v[208:211], v[232:235], v[80:83]
	v_mfma_f32_16x16x32_bf16 v[64:67], v[208:211], v[240:243], v[64:67]
	v_mfma_f32_16x16x32_bf16 v[64:67], v[212:215], v[244:247], v[64:67]
	v_mfma_f32_16x16x32_bf16 v[68:71], v[204:207], v[244:247], v[68:71]
	v_mfma_f32_16x16x32_bf16 v[68:71], v[200:203], v[240:243], v[68:71]
	s_barrier
	s_add_u32 s98, s76, 0x80
	s_addc_u32 s99, s77, 0
	s_add_u32 s100, s78, 0x80
	s_addc_u32 s101, s79, 0
	s_add_i32 s43, s3, s85
	s_mov_b32 m0, s43
	ds_read_b128 v[216:219], v159 offset:16384
	ds_read_b128 v[220:223], v159 offset:17408
	ds_read_b128 v[224:227], v159 offset:18432
	ds_read_b128 v[228:231], v159 offset:19456
	ds_read_b128 v[232:235], v159 offset:20480
	ds_read_b128 v[236:239], v159 offset:21504
	ds_read_b128 v[240:243], v159 offset:22528
	ds_read_b128 v[244:247], v159 offset:23552
	global_load_lds_dwordx4 v152, s[76:77]
	s_add_i32 m0, s43, 0x2000
	s_add_u32 s44, s76, 0x80000
	s_addc_u32 s45, s77, 0
	s_add_i32 s43, s52, s85
	global_load_lds_dwordx4 v156, s[76:77]
	s_mov_b32 m0, s43
	s_nop 0
	global_load_lds_dwordx4 v152, s[44:45]
	s_add_i32 m0, s43, 0x2000
	s_nop 0
	global_load_lds_dwordx4 v156, s[44:45]
	s_mov_b32 m0, s86
	s_nop 0
	global_load_lds_dwordx4 v150, s[78:79]
	s_mov_b32 m0, s87
	s_nop 0
	global_load_lds_dwordx4 v154, s[78:79]
	s_waitcnt vmcnt(8)
	s_waitcnt lgkmcnt(0)
	s_barrier
	v_mfma_f32_16x16x32_bf16 v[60:63], v[162:165], v[216:219], v[60:63]
	v_mfma_f32_16x16x32_bf16 v[60:63], v[166:169], v[220:223], v[60:63]
	v_mfma_f32_16x16x32_bf16 v[56:59], v[196:199], v[220:223], v[56:59]
	v_mfma_f32_16x16x32_bf16 v[56:59], v[172:175], v[216:219], v[56:59]
	v_mfma_f32_16x16x32_bf16 v[40:43], v[172:175], v[224:227], v[40:43]
	v_mfma_f32_16x16x32_bf16 v[40:43], v[196:199], v[228:231], v[40:43]
	v_mfma_f32_16x16x32_bf16 v[44:47], v[166:169], v[228:231], v[44:47]
	v_mfma_f32_16x16x32_bf16 v[44:47], v[162:165], v[224:227], v[44:47]
	v_mfma_f32_16x16x32_bf16 v[28:31], v[162:165], v[232:235], v[28:31]
	v_mfma_f32_16x16x32_bf16 v[28:31], v[166:169], v[236:239], v[28:31]
	v_mfma_f32_16x16x32_bf16 v[24:27], v[196:199], v[236:239], v[24:27]
	v_mfma_f32_16x16x32_bf16 v[24:27], v[172:175], v[232:235], v[24:27]
	v_mfma_f32_16x16x32_bf16 v[4:7], v[172:175], v[240:243], v[4:7]
	v_mfma_f32_16x16x32_bf16 v[4:7], v[196:199], v[244:247], v[4:7]
	v_mfma_f32_16x16x32_bf16 v[12:15], v[166:169], v[244:247], v[12:15]
	v_mfma_f32_16x16x32_bf16 v[12:15], v[162:165], v[240:243], v[12:15]
	v_mfma_f32_16x16x32_bf16 v[52:55], v[200:203], v[216:219], v[52:55]
	v_mfma_f32_16x16x32_bf16 v[52:55], v[204:207], v[220:223], v[52:55]
	v_mfma_f32_16x16x32_bf16 v[48:51], v[212:215], v[220:223], v[48:51]
	v_mfma_f32_16x16x32_bf16 v[48:51], v[208:211], v[216:219], v[48:51]
	v_mfma_f32_16x16x32_bf16 v[32:35], v[208:211], v[224:227], v[32:35]
	v_mfma_f32_16x16x32_bf16 v[32:35], v[212:215], v[228:231], v[32:35]
	v_mfma_f32_16x16x32_bf16 v[36:39], v[204:207], v[228:231], v[36:39]
	v_mfma_f32_16x16x32_bf16 v[36:39], v[200:203], v[224:227], v[36:39]
	v_mfma_f32_16x16x32_bf16 v[20:23], v[200:203], v[232:235], v[20:23]
	v_mfma_f32_16x16x32_bf16 v[20:23], v[204:207], v[236:239], v[20:23]
	v_mfma_f32_16x16x32_bf16 v[16:19], v[212:215], v[236:239], v[16:19]
	v_mfma_f32_16x16x32_bf16 v[16:19], v[208:211], v[232:235], v[16:19]
	v_mfma_f32_16x16x32_bf16 v[0:3], v[208:211], v[240:243], v[0:3]
	v_mfma_f32_16x16x32_bf16 v[0:3], v[212:215], v[244:247], v[0:3]
	v_mfma_f32_16x16x32_bf16 v[8:11], v[204:207], v[244:247], v[8:11]
	v_mfma_f32_16x16x32_bf16 v[8:11], v[200:203], v[240:243], v[8:11]
	s_barrier
; #define PG8_STAGE(bufoff, gbase, voff) do { _Pragma("unroll") for (int _i = 0; _i < 2; ++_i) \
;         __builtin_amdgcn_global_load_lds((const unsigned*)((const char*)(gbase) + (voff)[_i]), (PG8_LAS unsigned*)(lds + (bufoff) + ldsw + _i * 8192), 16, 0, 0); } while (0)
; #define PG8_LDA(dst, b, h) do { _Pragma("unroll") for (int m = 0; m < 4; ++m) _Pragma("unroll") for (int k = 0; k < 2; ++k) dst[m][k] = *(const PG8_LAS bf16x8*)(lds + PG8_SA(b, h) + aoff + m * 2048 + k * 1024); } while (0)
; #define PG8_LDB(dst, b, h) do { _Pragma("unroll") for (int n = 0; n < 2; ++n) _Pragma("unroll") for (int k = 0; k < 2; ++k) dst[n][k] = *(const PG8_LAS bf16x8*)(lds + PG8_SB(b, h) + boff + n * 2048 + k * 1024); } while (0)
; #define PG8_MMA(ai, bj, At, Bt) do { __builtin_amdgcn_s_setprio(1); _Pragma("unroll") for (int m = 0; m < 4; ++m) _Pragma("unroll") for (int n = 0; n < 2; ++n) _Pragma("unroll") for (int k = 0; k < 2; ++k) \
;         acc[ai][bj][m][n] = __builtin_amdgcn_mfma_f32_16x16x32_bf16(Bt[n][k], At[m][k], acc[ai][bj][m][n], 0, 0, 0); __builtin_amdgcn_s_setprio(0); } while (0)
; #define PG8_WAIT_V(n) asm volatile("s_waitcnt vmcnt(" #n ")" ::: "memory")
; #define PG8_WAIT_L(n) asm volatile("s_waitcnt lgkmcnt(" #n ")" ::: "memory")
; #define PG8_BAR __builtin_amdgcn_s_barrier()
; #define PG8_SCHED __builtin_amdgcn_sched_barrier(0)
;     __device__ __forceinline__ void operator()(const f32x4 (&acc)[2][2][4][2], const Unit& u, int wr, int wc, int fr, int fq) const {
;         const int row0 = u.pm * BM + wr * 64 + fr, pn = u.pn, cw = wc * 32 + 8 * fq;
;         if (pn >= 10) {
; template <class Epi, class Sched, bool ALIGN_EPI = false, bool SP2 = false>
; __device__ __forceinline__ void gemm_phase(PG8_LAS unsigned char* lds, const Gemm g, const Sched& S, const Epi& E) {
;     ...
;             PG8_LDB(B0, 1, 0); PG8_LDB(B1, 1, 1); PG8_SCHED; PG8_LDA(At, 1, 0); PG8_STAGE(PG8_SA(0, 1), a2 + hstep, voffA);
;             PG8_WAIT_V(8); PG8_WAIT_L(0); PG8_BAR; PG8_MMA(0, 0, At, B0); PG8_MMA(0, 1, At, B1); PG8_BAR; PG8_SCHED;
;             PG8_LDA(At, 1, 1); PG8_STAGE(PG8_SB(1, 0), b3, voffB); PG8_STAGE(PG8_SB(1, 1), b3 + hstep, voffB); PG8_STAGE(PG8_SA(1, 0), a3, voffA);
;             PG8_WAIT_V(8); PG8_WAIT_L(0); PG8_BAR; PG8_MMA(1, 0, At, B0); PG8_MMA(1, 1, At, B1); PG8_BAR; PG8_SCHED;
	s_add_i32 s43, 0, 0x18000
	v_add_u32_e32 v128, s43, v145
	s_add_i32 s46, 0, 0x1c000
	ds_read_b128 v[162:165], v128
	ds_read_b128 v[166:169], v128 offset:1024
	ds_read_b128 v[172:175], v128 offset:2048
	ds_read_b128 v[196:199], v128 offset:3072
	v_add_u32_e32 v128, s46, v145
	ds_read_b128 v[200:203], v128
	ds_read_b128 v[204:207], v128 offset:1024
	ds_read_b128 v[208:211], v128 offset:2048
	ds_read_b128 v[212:215], v128 offset:3072
	s_add_u32 s44, s78, 0x80000
	s_addc_u32 s45, s79, 0
	s_mov_b32 m0, s91
	ds_read_b128 v[216:219], v159 offset:32768
	ds_read_b128 v[220:223], v159 offset:33792
	ds_read_b128 v[224:227], v159 offset:34816
	ds_read_b128 v[228:231], v159 offset:35840
	ds_read_b128 v[232:235], v159 offset:36864
	ds_read_b128 v[236:239], v159 offset:37888
	ds_read_b128 v[240:243], v159 offset:38912
	ds_read_b128 v[244:247], v159 offset:39936
	global_load_lds_dwordx4 v150, s[44:45]
	s_mov_b32 m0, s92
	s_nop 0
	global_load_lds_dwordx4 v154, s[44:45]
	s_waitcnt vmcnt(8)
	s_waitcnt lgkmcnt(0)
	s_barrier
	v_mfma_f32_16x16x32_bf16 v[124:127], v[162:165], v[216:219], v[124:127]
	v_mfma_f32_16x16x32_bf16 v[124:127], v[166:169], v[220:223], v[124:127]
	v_mfma_f32_16x16x32_bf16 v[120:123], v[196:199], v[220:223], v[120:123]
	v_mfma_f32_16x16x32_bf16 v[120:123], v[172:175], v[216:219], v[120:123]
	v_mfma_f32_16x16x32_bf16 v[104:107], v[172:175], v[224:227], v[104:107]
	v_mfma_f32_16x16x32_bf16 v[104:107], v[196:199], v[228:231], v[104:107]
	v_mfma_f32_16x16x32_bf16 v[108:111], v[166:169], v[228:231], v[108:111]
	v_mfma_f32_16x16x32_bf16 v[108:111], v[162:165], v[224:227], v[108:111]
	v_mfma_f32_16x16x32_bf16 v[92:95], v[162:165], v[232:235], v[92:95]
	v_mfma_f32_16x16x32_bf16 v[92:95], v[166:169], v[236:239], v[92:95]
	v_mfma_f32_16x16x32_bf16 v[88:91], v[196:199], v[236:239], v[88:91]
	v_mfma_f32_16x16x32_bf16 v[88:91], v[172:175], v[232:235], v[88:91]
	v_mfma_f32_16x16x32_bf16 v[72:75], v[172:175], v[240:243], v[72:75]
	v_mfma_f32_16x16x32_bf16 v[72:75], v[196:199], v[244:247], v[72:75]
	v_mfma_f32_16x16x32_bf16 v[76:79], v[166:169], v[244:247], v[76:79]
	v_mfma_f32_16x16x32_bf16 v[76:79], v[162:165], v[240:243], v[76:79]
	v_mfma_f32_16x16x32_bf16 v[116:119], v[200:203], v[216:219], v[116:119]
	v_mfma_f32_16x16x32_bf16 v[116:119], v[204:207], v[220:223], v[116:119]
	v_mfma_f32_16x16x32_bf16 v[112:115], v[212:215], v[220:223], v[112:115]
	v_mfma_f32_16x16x32_bf16 v[112:115], v[208:211], v[216:219], v[112:115]
	v_mfma_f32_16x16x32_bf16 v[96:99], v[208:211], v[224:227], v[96:99]
	v_mfma_f32_16x16x32_bf16 v[96:99], v[212:215], v[228:231], v[96:99]
	v_mfma_f32_16x16x32_bf16 v[100:103], v[204:207], v[228:231], v[100:103]
	v_mfma_f32_16x16x32_bf16 v[100:103], v[200:203], v[224:227], v[100:103]
	v_mfma_f32_16x16x32_bf16 v[84:87], v[200:203], v[232:235], v[84:87]
	v_mfma_f32_16x16x32_bf16 v[84:87], v[204:207], v[236:239], v[84:87]
	v_mfma_f32_16x16x32_bf16 v[80:83], v[212:215], v[236:239], v[80:83]
	v_mfma_f32_16x16x32_bf16 v[80:83], v[208:211], v[232:235], v[80:83]
	v_mfma_f32_16x16x32_bf16 v[64:67], v[208:211], v[240:243], v[64:67]
	v_mfma_f32_16x16x32_bf16 v[64:67], v[212:215], v[244:247], v[64:67]
	v_mfma_f32_16x16x32_bf16 v[68:71], v[204:207], v[244:247], v[68:71]
	v_mfma_f32_16x16x32_bf16 v[68:71], v[200:203], v[240:243], v[68:71]
	s_barrier
	s_add_i32 s43, s43, s85
	s_mov_b32 m0, s43
	ds_read_b128 v[216:219], v159 offset:49152
	ds_read_b128 v[220:223], v159 offset:50176
	ds_read_b128 v[224:227], v159 offset:51200
	ds_read_b128 v[228:231], v159 offset:52224
	ds_read_b128 v[232:235], v159 offset:53248
	ds_read_b128 v[236:239], v159 offset:54272
	ds_read_b128 v[240:243], v159 offset:55296
	ds_read_b128 v[244:247], v159 offset:56320
	global_load_lds_dwordx4 v152, s[98:99]
	s_add_i32 m0, s43, 0x2000
	s_add_u32 s44, s76, 0x80080
	s_addc_u32 s45, s77, 0
	s_add_i32 s43, s46, s85
	global_load_lds_dwordx4 v156, s[98:99]
	s_mov_b32 m0, s43
	s_nop 0
	global_load_lds_dwordx4 v152, s[44:45]
	s_add_i32 m0, s43, 0x2000
	s_nop 0
	global_load_lds_dwordx4 v156, s[44:45]
	s_mov_b32 m0, s93
	s_nop 0
	global_load_lds_dwordx4 v150, s[100:101]
	s_mov_b32 m0, s94
	s_nop 0
	global_load_lds_dwordx4 v154, s[100:101]
	s_waitcnt vmcnt(8)
	s_waitcnt lgkmcnt(0)
	s_barrier
	v_mfma_f32_16x16x32_bf16 v[60:63], v[162:165], v[216:219], v[60:63]
	v_mfma_f32_16x16x32_bf16 v[60:63], v[166:169], v[220:223], v[60:63]
	v_mfma_f32_16x16x32_bf16 v[56:59], v[196:199], v[220:223], v[56:59]
	v_mfma_f32_16x16x32_bf16 v[56:59], v[172:175], v[216:219], v[56:59]
	v_mfma_f32_16x16x32_bf16 v[40:43], v[172:175], v[224:227], v[40:43]
	v_mfma_f32_16x16x32_bf16 v[40:43], v[196:199], v[228:231], v[40:43]
	v_mfma_f32_16x16x32_bf16 v[44:47], v[166:169], v[228:231], v[44:47]
	v_mfma_f32_16x16x32_bf16 v[44:47], v[162:165], v[224:227], v[44:47]
	v_mfma_f32_16x16x32_bf16 v[28:31], v[162:165], v[232:235], v[28:31]
	v_mfma_f32_16x16x32_bf16 v[28:31], v[166:169], v[236:239], v[28:31]
	v_mfma_f32_16x16x32_bf16 v[24:27], v[196:199], v[236:239], v[24:27]
	v_mfma_f32_16x16x32_bf16 v[24:27], v[172:175], v[232:235], v[24:27]
	v_mfma_f32_16x16x32_bf16 v[4:7], v[172:175], v[240:243], v[4:7]
	v_mfma_f32_16x16x32_bf16 v[4:7], v[196:199], v[244:247], v[4:7]
	v_mfma_f32_16x16x32_bf16 v[12:15], v[166:169], v[244:247], v[12:15]
	v_mfma_f32_16x16x32_bf16 v[12:15], v[162:165], v[240:243], v[12:15]
	v_mfma_f32_16x16x32_bf16 v[52:55], v[200:203], v[216:219], v[52:55]
	v_mfma_f32_16x16x32_bf16 v[52:55], v[204:207], v[220:223], v[52:55]
	v_mfma_f32_16x16x32_bf16 v[48:51], v[212:215], v[220:223], v[48:51]
	v_mfma_f32_16x16x32_bf16 v[48:51], v[208:211], v[216:219], v[48:51]
	v_mfma_f32_16x16x32_bf16 v[32:35], v[208:211], v[224:227], v[32:35]
	v_mfma_f32_16x16x32_bf16 v[32:35], v[212:215], v[228:231], v[32:35]
	v_mfma_f32_16x16x32_bf16 v[36:39], v[204:207], v[228:231], v[36:39]
	v_mfma_f32_16x16x32_bf16 v[36:39], v[200:203], v[224:227], v[36:39]
	v_mfma_f32_16x16x32_bf16 v[20:23], v[200:203], v[232:235], v[20:23]
	v_mfma_f32_16x16x32_bf16 v[20:23], v[204:207], v[236:239], v[20:23]
	v_mfma_f32_16x16x32_bf16 v[16:19], v[212:215], v[236:239], v[16:19]
	v_mfma_f32_16x16x32_bf16 v[16:19], v[208:211], v[232:235], v[16:19]
	v_mfma_f32_16x16x32_bf16 v[0:3], v[208:211], v[240:243], v[0:3]
	v_mfma_f32_16x16x32_bf16 v[0:3], v[212:215], v[244:247], v[0:3]
	v_mfma_f32_16x16x32_bf16 v[8:11], v[204:207], v[244:247], v[8:11]
	v_mfma_f32_16x16x32_bf16 v[8:11], v[200:203], v[240:243], v[8:11]
	s_barrier
	s_add_i32 s42, s42, 2
	s_add_u32 s10, s10, 0x100
	s_addc_u32 s11, s11, 0
	s_add_u32 s40, s40, 0x100
	s_addc_u32 s41, s41, 0
	s_cmp_gt_u32 s42, 29
	s_cbranch_scc0 .LBB0_623
	s_setprio 0
	s_and_b64 vcc, exec, s[66:67]
	s_cbranch_vccz .LBB0_628
	s_barrier
	v_lshl_add_u32 v162, s4, 8, v143
	s_cmp_lt_i32 s55, 10
	s_mov_b64 s[10:11], -1
	s_cbranch_scc1 .LBB0_629

;     __device__ __forceinline__ bool next(int i, Unit& u) const { if (i > 0 || c >= nitems) return false; u.pm = 64; u.pn = c % npn; u.k0 = (c / npn) * kslice; return true; }
; #define PG8_STAGE(bufoff, gbase, voff) do { _Pragma("unroll") for (int _i = 0; _i < 2; ++_i) \
;         __builtin_amdgcn_global_load_lds((const unsigned*)((const char*)(gbase) + (voff)[_i]), (PG8_LAS unsigned*)(lds + (bufoff) + ldsw + _i * 8192), 16, 0, 0); } while (0)
; #define PG8_LDA(dst, b, h) do { _Pragma("unroll") for (int m = 0; m < 4; ++m) _Pragma("unroll") for (int k = 0; k < 2; ++k) dst[m][k] = *(const PG8_LAS bf16x8*)(lds + PG8_SA(b, h) + aoff + m * 2048 + k * 1024); } while (0)
; #define PG8_LDB(dst, b, h) do { _Pragma("unroll") for (int n = 0; n < 2; ++n) _Pragma("unroll") for (int k = 0; k < 2; ++k) dst[n][k] = *(const PG8_LAS bf16x8*)(lds + PG8_SB(b, h) + boff + n * 2048 + k * 1024); } while (0)
; #define PG8_WAIT_V(n) asm volatile("s_waitcnt vmcnt(" #n ")" ::: "memory")
; template <class Epi, class Sched, bool ALIGN_EPI = false, bool SP2 = false>
; __device__ __forceinline__ void gemm_phase(PG8_LAS unsigned char* lds, const Gemm g, const Sched& S, const Epi& E) {
;     ...
;         const bool has_next = S.next(ui + 1, nxt);
;         const char* nA = has_next ? (const char*)g.A + (size_t)nxt.pm * tstep + (size_t)nxt.k0 * 2 : cA; const char* nB = has_next ? (const char*)g.Bt + (size_t)nxt.pn * tstep + (size_t)nxt.k0 * 2 : cB;
;         for (int t = 0; t < nt; t += 2) {
;             const bool last = (t == nt - 2);
;             const char* a1 = cA + (size_t)(t + 1) * kstep;
;             const char* a2 = last ? nA : cA + (size_t)(t + 2) * kstep; const char* b2 = last ? nB : cB + (size_t)(t + 2) * kstep;
;             const char* a3 = a2 + kstep; const char* b3 = b2 + kstep;
;             if (last && has_next) S.a_ready(nxt);
;             if constexpr (SP2) {
;             PG8_LDB(B0, 0, 0); PG8_LDB(B1, 0, 1); PG8_SCHED; PG8_LDA(At, 0, 0); PG8_STAGE(PG8_SA(1, 1), a1 + hstep, voffA);
;             PG8_WAIT_V(8); PG8_WAIT_L(0); PG8_BAR; PG8_MMA(0, 0, At, B0); PG8_MMA(0, 1, At, B1); PG8_BAR; PG8_SCHED;
;             PG8_LDA(At, 0, 1); PG8_STAGE(PG8_SB(0, 0), b2, voffB); PG8_STAGE(PG8_SB(0, 1), b2 + hstep, voffB); PG8_STAGE(PG8_SA(0, 0), a2, voffA);
;             PG8_WAIT_V(8); PG8_WAIT_L(0); PG8_BAR; PG8_MMA(1, 0, At, B0); PG8_MMA(1, 1, At, B1); PG8_BAR; PG8_SCHED;
.Lsp_skip_3:
.LBB0_1056:
	ds_read_b128 v[128:131], v149
	ds_read_b128 v[132:135], v149 offset:1024
	ds_read_b128 v[172:175], v149 offset:2048
	ds_read_b128 v[188:191], v149 offset:3072
	ds_read_b128 v[192:195], v159
	ds_read_b128 v[196:199], v159 offset:1024
	ds_read_b128 v[200:203], v159 offset:2048
	ds_read_b128 v[204:207], v159 offset:3072
	s_add_u32 s40, s38, 0xfff80080
	s_addc_u32 s41, s39, -1
	s_cmp_eq_u32 s65, 28
	s_cselect_b32 s43, s27, s41
	s_cselect_b32 s42, s35, s40
	s_cselect_b32 s41, s25, s64
	s_cselect_b32 s40, s37, s63
	s_add_i32 m0, s46, 0xc000
	ds_read_b128 v[208:211], v163
	ds_read_b128 v[212:215], v163 offset:1024
	ds_read_b128 v[216:219], v163 offset:2048
	ds_read_b128 v[220:223], v163 offset:3072
	ds_read_b128 v[224:227], v163 offset:4096
	ds_read_b128 v[228:231], v163 offset:5120
	ds_read_b128 v[232:235], v163 offset:6144
	ds_read_b128 v[236:239], v163 offset:7168
	global_load_lds_dwordx4 v164, s[38:39]
	s_add_i32 m0, s46, 0xe000
	s_nop 0
	global_load_lds_dwordx4 v166, s[38:39]
	s_waitcnt vmcnt(8)
	s_waitcnt lgkmcnt(0)
	s_barrier
	v_mfma_f32_16x16x32_bf16 v[124:127], v[128:131], v[208:211], v[124:127]
	v_mfma_f32_16x16x32_bf16 v[124:127], v[132:135], v[212:215], v[124:127]
	v_mfma_f32_16x16x32_bf16 v[120:123], v[188:191], v[212:215], v[120:123]
	v_mfma_f32_16x16x32_bf16 v[120:123], v[172:175], v[208:211], v[120:123]
	v_mfma_f32_16x16x32_bf16 v[104:107], v[172:175], v[216:219], v[104:107]
	v_mfma_f32_16x16x32_bf16 v[104:107], v[188:191], v[220:223], v[104:107]
	v_mfma_f32_16x16x32_bf16 v[108:111], v[132:135], v[220:223], v[108:111]
	v_mfma_f32_16x16x32_bf16 v[108:111], v[128:131], v[216:219], v[108:111]
	v_mfma_f32_16x16x32_bf16 v[92:95], v[128:131], v[224:227], v[92:95]
	v_mfma_f32_16x16x32_bf16 v[92:95], v[132:135], v[228:231], v[92:95]
	v_mfma_f32_16x16x32_bf16 v[88:91], v[188:191], v[228:231], v[88:91]
	v_mfma_f32_16x16x32_bf16 v[88:91], v[172:175], v[224:227], v[88:91]
	v_mfma_f32_16x16x32_bf16 v[72:75], v[172:175], v[232:235], v[72:75]
	v_mfma_f32_16x16x32_bf16 v[72:75], v[188:191], v[236:239], v[72:75]
	v_mfma_f32_16x16x32_bf16 v[76:79], v[132:135], v[236:239], v[76:79]
	v_mfma_f32_16x16x32_bf16 v[76:79], v[128:131], v[232:235], v[76:79]
	v_mfma_f32_16x16x32_bf16 v[116:119], v[192:195], v[208:211], v[116:119]
	v_mfma_f32_16x16x32_bf16 v[116:119], v[196:199], v[212:215], v[116:119]
	v_mfma_f32_16x16x32_bf16 v[112:115], v[204:207], v[212:215], v[112:115]
	v_mfma_f32_16x16x32_bf16 v[112:115], v[200:203], v[208:211], v[112:115]
	v_mfma_f32_16x16x32_bf16 v[96:99], v[200:203], v[216:219], v[96:99]
	v_mfma_f32_16x16x32_bf16 v[96:99], v[204:207], v[220:223], v[96:99]
	v_mfma_f32_16x16x32_bf16 v[100:103], v[196:199], v[220:223], v[100:103]
	v_mfma_f32_16x16x32_bf16 v[100:103], v[192:195], v[216:219], v[100:103]
	v_mfma_f32_16x16x32_bf16 v[84:87], v[192:195], v[224:227], v[84:87]
	v_mfma_f32_16x16x32_bf16 v[84:87], v[196:199], v[228:231], v[84:87]
	v_mfma_f32_16x16x32_bf16 v[80:83], v[204:207], v[228:231], v[80:83]
	v_mfma_f32_16x16x32_bf16 v[80:83], v[200:203], v[224:227], v[80:83]
	v_mfma_f32_16x16x32_bf16 v[64:67], v[200:203], v[232:235], v[64:67]
	v_mfma_f32_16x16x32_bf16 v[64:67], v[204:207], v[236:239], v[64:67]
	v_mfma_f32_16x16x32_bf16 v[68:71], v[196:199], v[236:239], v[68:71]
	v_mfma_f32_16x16x32_bf16 v[68:71], v[192:195], v[232:235], v[68:71]
	s_barrier
	s_add_u32 s98, s40, 0x80
	s_addc_u32 s99, s41, 0
	s_add_u32 s100, s42, 0x80
	s_addc_u32 s101, s43, 0
	s_add_i32 s66, s56, s45
	s_mov_b32 m0, s66
	ds_read_b128 v[208:211], v163 offset:16384
	ds_read_b128 v[212:215], v163 offset:17408
	ds_read_b128 v[216:219], v163 offset:18432
	ds_read_b128 v[220:223], v163 offset:19456
	ds_read_b128 v[224:227], v163 offset:20480
	ds_read_b128 v[228:231], v163 offset:21504
	ds_read_b128 v[232:235], v163 offset:22528
	ds_read_b128 v[236:239], v163 offset:23552
	global_load_lds_dwordx4 v152, s[40:41]
	s_add_i32 m0, s66, 0x2000
	s_add_u32 s66, s40, 0x80000
	s_addc_u32 s67, s41, 0
	s_add_i32 s68, s57, s45
	global_load_lds_dwordx4 v156, s[40:41]
	s_mov_b32 m0, s68
	s_nop 0
	global_load_lds_dwordx4 v152, s[66:67]
	s_add_i32 m0, s68, 0x2000
	s_nop 0
	global_load_lds_dwordx4 v156, s[66:67]
	s_mov_b32 m0, s46
	s_nop 0
	global_load_lds_dwordx4 v150, s[42:43]
	s_mov_b32 m0, s47
	s_nop 0
	global_load_lds_dwordx4 v154, s[42:43]
	s_waitcnt vmcnt(8)
	s_waitcnt lgkmcnt(0)
	s_barrier
	v_mfma_f32_16x16x32_bf16 v[60:63], v[128:131], v[208:211], v[60:63]
	v_mfma_f32_16x16x32_bf16 v[60:63], v[132:135], v[212:215], v[60:63]
	v_mfma_f32_16x16x32_bf16 v[56:59], v[188:191], v[212:215], v[56:59]
	v_mfma_f32_16x16x32_bf16 v[56:59], v[172:175], v[208:211], v[56:59]
	v_mfma_f32_16x16x32_bf16 v[40:43], v[172:175], v[216:219], v[40:43]
	v_mfma_f32_16x16x32_bf16 v[40:43], v[188:191], v[220:223], v[40:43]
	v_mfma_f32_16x16x32_bf16 v[44:47], v[132:135], v[220:223], v[44:47]
	v_mfma_f32_16x16x32_bf16 v[44:47], v[128:131], v[216:219], v[44:47]
	v_mfma_f32_16x16x32_bf16 v[28:31], v[128:131], v[224:227], v[28:31]
	v_mfma_f32_16x16x32_bf16 v[28:31], v[132:135], v[228:231], v[28:31]
	v_mfma_f32_16x16x32_bf16 v[24:27], v[188:191], v[228:231], v[24:27]
	v_mfma_f32_16x16x32_bf16 v[24:27], v[172:175], v[224:227], v[24:27]
	v_mfma_f32_16x16x32_bf16 v[8:11], v[172:175], v[232:235], v[8:11]
	v_mfma_f32_16x16x32_bf16 v[8:11], v[188:191], v[236:239], v[8:11]
	v_mfma_f32_16x16x32_bf16 v[12:15], v[132:135], v[236:239], v[12:15]
	v_mfma_f32_16x16x32_bf16 v[12:15], v[128:131], v[232:235], v[12:15]
	v_mfma_f32_16x16x32_bf16 v[52:55], v[192:195], v[208:211], v[52:55]
	v_mfma_f32_16x16x32_bf16 v[52:55], v[196:199], v[212:215], v[52:55]
	v_mfma_f32_16x16x32_bf16 v[48:51], v[204:207], v[212:215], v[48:51]
	v_mfma_f32_16x16x32_bf16 v[48:51], v[200:203], v[208:211], v[48:51]
	v_mfma_f32_16x16x32_bf16 v[32:35], v[200:203], v[216:219], v[32:35]
	v_mfma_f32_16x16x32_bf16 v[32:35], v[204:207], v[220:223], v[32:35]
	v_mfma_f32_16x16x32_bf16 v[36:39], v[196:199], v[220:223], v[36:39]
	v_mfma_f32_16x16x32_bf16 v[36:39], v[192:195], v[216:219], v[36:39]
	v_mfma_f32_16x16x32_bf16 v[20:23], v[192:195], v[224:227], v[20:23]
	v_mfma_f32_16x16x32_bf16 v[20:23], v[196:199], v[228:231], v[20:23]
	v_mfma_f32_16x16x32_bf16 v[16:19], v[204:207], v[228:231], v[16:19]
	v_mfma_f32_16x16x32_bf16 v[16:19], v[200:203], v[224:227], v[16:19]
	v_mfma_f32_16x16x32_bf16 v[0:3], v[200:203], v[232:235], v[0:3]
	v_mfma_f32_16x16x32_bf16 v[0:3], v[204:207], v[236:239], v[0:3]
	v_mfma_f32_16x16x32_bf16 v[4:7], v[196:199], v[236:239], v[4:7]
	v_mfma_f32_16x16x32_bf16 v[4:7], v[192:195], v[232:235], v[4:7]
	s_barrier
; #define PG8_STAGE(bufoff, gbase, voff) do { _Pragma("unroll") for (int _i = 0; _i < 2; ++_i) \
;         __builtin_amdgcn_global_load_lds((const unsigned*)((const char*)(gbase) + (voff)[_i]), (PG8_LAS unsigned*)(lds + (bufoff) + ldsw + _i * 8192), 16, 0, 0); } while (0)
; #define PG8_LDA(dst, b, h) do { _Pragma("unroll") for (int m = 0; m < 4; ++m) _Pragma("unroll") for (int k = 0; k < 2; ++k) dst[m][k] = *(const PG8_LAS bf16x8*)(lds + PG8_SA(b, h) + aoff + m * 2048 + k * 1024); } while (0)
; #define PG8_LDB(dst, b, h) do { _Pragma("unroll") for (int n = 0; n < 2; ++n) _Pragma("unroll") for (int k = 0; k < 2; ++k) dst[n][k] = *(const PG8_LAS bf16x8*)(lds + PG8_SB(b, h) + boff + n * 2048 + k * 1024); } while (0)
; #define PG8_MMA(ai, bj, At, Bt) do { __builtin_amdgcn_s_setprio(1); _Pragma("unroll") for (int m = 0; m < 4; ++m) _Pragma("unroll") for (int n = 0; n < 2; ++n) _Pragma("unroll") for (int k = 0; k < 2; ++k) \
;         acc[ai][bj][m][n] = __builtin_amdgcn_mfma_f32_16x16x32_bf16(Bt[n][k], At[m][k], acc[ai][bj][m][n], 0, 0, 0); __builtin_amdgcn_s_setprio(0); } while (0)
; #define PG8_WAIT_V(n) asm volatile("s_waitcnt vmcnt(" #n ")" ::: "memory")
; #define PG8_WAIT_L(n) asm volatile("s_waitcnt lgkmcnt(" #n ")" ::: "memory")
; #define PG8_BAR __builtin_amdgcn_s_barrier()
; #define PG8_SCHED __builtin_amdgcn_sched_barrier(0)
; template <class Epi, class Sched, bool ALIGN_EPI = false, bool SP2 = false>
; __device__ __forceinline__ void gemm_phase(PG8_LAS unsigned char* lds, const Gemm g, const Sched& S, const Epi& E) {
;     ...
;             PG8_LDB(B0, 1, 0); PG8_LDB(B1, 1, 1); PG8_SCHED; PG8_LDA(At, 1, 0); PG8_STAGE(PG8_SA(0, 1), a2 + hstep, voffA);
;             PG8_WAIT_V(8); PG8_WAIT_L(0); PG8_BAR; PG8_MMA(0, 0, At, B0); PG8_MMA(0, 1, At, B1); PG8_BAR; PG8_SCHED;
;             PG8_LDA(At, 1, 1); PG8_STAGE(PG8_SB(1, 0), b3, voffB); PG8_STAGE(PG8_SB(1, 1), b3 + hstep, voffB); PG8_STAGE(PG8_SA(1, 0), a3, voffA);
;             PG8_WAIT_V(8); PG8_WAIT_L(0); PG8_BAR; PG8_MMA(1, 0, At, B0); PG8_MMA(1, 1, At, B1); PG8_BAR; PG8_SCHED;
	s_add_i32 s66, 0, 0x18000
	v_add_u32_e32 v160, s66, v145
	s_add_i32 s67, 0, 0x1c000
	ds_read_b128 v[128:131], v160
	ds_read_b128 v[132:135], v160 offset:1024
	ds_read_b128 v[172:175], v160 offset:2048
	ds_read_b128 v[188:191], v160 offset:3072
	v_add_u32_e32 v160, s67, v145
	ds_read_b128 v[192:195], v160
	ds_read_b128 v[196:199], v160 offset:1024
	ds_read_b128 v[200:203], v160 offset:2048
	ds_read_b128 v[204:207], v160 offset:3072
	s_add_u32 s42, s42, 0x80000
	s_addc_u32 s43, s43, 0
	s_mov_b32 m0, s48
	ds_read_b128 v[208:211], v163 offset:32768
	ds_read_b128 v[212:215], v163 offset:33792
	ds_read_b128 v[216:219], v163 offset:34816
	ds_read_b128 v[220:223], v163 offset:35840
	ds_read_b128 v[224:227], v163 offset:36864
	ds_read_b128 v[228:231], v163 offset:37888
	ds_read_b128 v[232:235], v163 offset:38912
	ds_read_b128 v[236:239], v163 offset:39936
	global_load_lds_dwordx4 v150, s[42:43]
	s_mov_b32 m0, s49
	s_nop 0
	global_load_lds_dwordx4 v154, s[42:43]
	s_waitcnt vmcnt(8)
	s_waitcnt lgkmcnt(0)
	s_barrier
	v_mfma_f32_16x16x32_bf16 v[124:127], v[128:131], v[208:211], v[124:127]
	v_mfma_f32_16x16x32_bf16 v[124:127], v[132:135], v[212:215], v[124:127]
	v_mfma_f32_16x16x32_bf16 v[120:123], v[188:191], v[212:215], v[120:123]
	v_mfma_f32_16x16x32_bf16 v[120:123], v[172:175], v[208:211], v[120:123]
	v_mfma_f32_16x16x32_bf16 v[104:107], v[172:175], v[216:219], v[104:107]
	v_mfma_f32_16x16x32_bf16 v[104:107], v[188:191], v[220:223], v[104:107]
	v_mfma_f32_16x16x32_bf16 v[108:111], v[132:135], v[220:223], v[108:111]
	v_mfma_f32_16x16x32_bf16 v[108:111], v[128:131], v[216:219], v[108:111]
	v_mfma_f32_16x16x32_bf16 v[92:95], v[128:131], v[224:227], v[92:95]
	v_mfma_f32_16x16x32_bf16 v[92:95], v[132:135], v[228:231], v[92:95]
	v_mfma_f32_16x16x32_bf16 v[88:91], v[188:191], v[228:231], v[88:91]
	v_mfma_f32_16x16x32_bf16 v[88:91], v[172:175], v[224:227], v[88:91]
	v_mfma_f32_16x16x32_bf16 v[72:75], v[172:175], v[232:235], v[72:75]
	v_mfma_f32_16x16x32_bf16 v[72:75], v[188:191], v[236:239], v[72:75]
	v_mfma_f32_16x16x32_bf16 v[76:79], v[132:135], v[236:239], v[76:79]
	v_mfma_f32_16x16x32_bf16 v[76:79], v[128:131], v[232:235], v[76:79]
	v_mfma_f32_16x16x32_bf16 v[116:119], v[192:195], v[208:211], v[116:119]
	v_mfma_f32_16x16x32_bf16 v[116:119], v[196:199], v[212:215], v[116:119]
	v_mfma_f32_16x16x32_bf16 v[112:115], v[204:207], v[212:215], v[112:115]
	v_mfma_f32_16x16x32_bf16 v[112:115], v[200:203], v[208:211], v[112:115]
	v_mfma_f32_16x16x32_bf16 v[96:99], v[200:203], v[216:219], v[96:99]
	v_mfma_f32_16x16x32_bf16 v[96:99], v[204:207], v[220:223], v[96:99]
	v_mfma_f32_16x16x32_bf16 v[100:103], v[196:199], v[220:223], v[100:103]
	v_mfma_f32_16x16x32_bf16 v[100:103], v[192:195], v[216:219], v[100:103]
	v_mfma_f32_16x16x32_bf16 v[84:87], v[192:195], v[224:227], v[84:87]
	v_mfma_f32_16x16x32_bf16 v[84:87], v[196:199], v[228:231], v[84:87]
	v_mfma_f32_16x16x32_bf16 v[80:83], v[204:207], v[228:231], v[80:83]
	v_mfma_f32_16x16x32_bf16 v[80:83], v[200:203], v[224:227], v[80:83]
	v_mfma_f32_16x16x32_bf16 v[64:67], v[200:203], v[232:235], v[64:67]
	v_mfma_f32_16x16x32_bf16 v[64:67], v[204:207], v[236:239], v[64:67]
	v_mfma_f32_16x16x32_bf16 v[68:71], v[196:199], v[236:239], v[68:71]
	v_mfma_f32_16x16x32_bf16 v[68:71], v[192:195], v[232:235], v[68:71]
	s_barrier
	s_add_i32 s42, s66, s45
	s_mov_b32 m0, s42
	ds_read_b128 v[208:211], v163 offset:49152
	ds_read_b128 v[212:215], v163 offset:50176
	ds_read_b128 v[216:219], v163 offset:51200
	ds_read_b128 v[220:223], v163 offset:52224
	ds_read_b128 v[224:227], v163 offset:53248
	ds_read_b128 v[228:231], v163 offset:54272
	ds_read_b128 v[232:235], v163 offset:55296
	ds_read_b128 v[236:239], v163 offset:56320
	global_load_lds_dwordx4 v152, s[98:99]
	s_add_i32 m0, s42, 0x2000
	s_add_u32 s40, s40, 0x80080
	s_addc_u32 s41, s41, 0
	s_add_i32 s42, s67, s45
	global_load_lds_dwordx4 v156, s[98:99]
	s_mov_b32 m0, s42
	s_nop 0
	global_load_lds_dwordx4 v152, s[40:41]
	s_add_i32 m0, s42, 0x2000
	s_nop 0
	global_load_lds_dwordx4 v156, s[40:41]
	s_mov_b32 m0, s51
	s_nop 0
	global_load_lds_dwordx4 v150, s[100:101]
	s_mov_b32 m0, s52
	s_nop 0
	global_load_lds_dwordx4 v154, s[100:101]
	s_waitcnt vmcnt(8)
	s_waitcnt lgkmcnt(0)
	s_barrier
	v_mfma_f32_16x16x32_bf16 v[60:63], v[128:131], v[208:211], v[60:63]
	v_mfma_f32_16x16x32_bf16 v[60:63], v[132:135], v[212:215], v[60:63]
	v_mfma_f32_16x16x32_bf16 v[56:59], v[188:191], v[212:215], v[56:59]
	v_mfma_f32_16x16x32_bf16 v[56:59], v[172:175], v[208:211], v[56:59]
	v_mfma_f32_16x16x32_bf16 v[40:43], v[172:175], v[216:219], v[40:43]
	v_mfma_f32_16x16x32_bf16 v[40:43], v[188:191], v[220:223], v[40:43]
	v_mfma_f32_16x16x32_bf16 v[44:47], v[132:135], v[220:223], v[44:47]
	v_mfma_f32_16x16x32_bf16 v[44:47], v[128:131], v[216:219], v[44:47]
	v_mfma_f32_16x16x32_bf16 v[28:31], v[128:131], v[224:227], v[28:31]
	v_mfma_f32_16x16x32_bf16 v[28:31], v[132:135], v[228:231], v[28:31]
	v_mfma_f32_16x16x32_bf16 v[24:27], v[188:191], v[228:231], v[24:27]
	v_mfma_f32_16x16x32_bf16 v[24:27], v[172:175], v[224:227], v[24:27]
	v_mfma_f32_16x16x32_bf16 v[8:11], v[172:175], v[232:235], v[8:11]
	v_mfma_f32_16x16x32_bf16 v[8:11], v[188:191], v[236:239], v[8:11]
	v_mfma_f32_16x16x32_bf16 v[12:15], v[132:135], v[236:239], v[12:15]
	v_mfma_f32_16x16x32_bf16 v[12:15], v[128:131], v[232:235], v[12:15]
	v_mfma_f32_16x16x32_bf16 v[52:55], v[192:195], v[208:211], v[52:55]
	v_mfma_f32_16x16x32_bf16 v[52:55], v[196:199], v[212:215], v[52:55]
	v_mfma_f32_16x16x32_bf16 v[48:51], v[204:207], v[212:215], v[48:51]
	v_mfma_f32_16x16x32_bf16 v[48:51], v[200:203], v[208:211], v[48:51]
	v_mfma_f32_16x16x32_bf16 v[32:35], v[200:203], v[216:219], v[32:35]
	v_mfma_f32_16x16x32_bf16 v[32:35], v[204:207], v[220:223], v[32:35]
	v_mfma_f32_16x16x32_bf16 v[36:39], v[196:199], v[220:223], v[36:39]
	v_mfma_f32_16x16x32_bf16 v[36:39], v[192:195], v[216:219], v[36:39]
	v_mfma_f32_16x16x32_bf16 v[20:23], v[192:195], v[224:227], v[20:23]
	v_mfma_f32_16x16x32_bf16 v[20:23], v[196:199], v[228:231], v[20:23]
	v_mfma_f32_16x16x32_bf16 v[16:19], v[204:207], v[228:231], v[16:19]
	v_mfma_f32_16x16x32_bf16 v[16:19], v[200:203], v[224:227], v[16:19]
	v_mfma_f32_16x16x32_bf16 v[0:3], v[200:203], v[232:235], v[0:3]
	v_mfma_f32_16x16x32_bf16 v[0:3], v[204:207], v[236:239], v[0:3]
	v_mfma_f32_16x16x32_bf16 v[4:7], v[196:199], v[236:239], v[4:7]
	v_mfma_f32_16x16x32_bf16 v[4:7], v[192:195], v[232:235], v[4:7]
	s_barrier
	s_add_i32 s65, s65, 2
	s_add_u32 s38, s38, 0x100
	s_addc_u32 s39, s39, 0
	s_add_u32 s63, s63, 0x100
	s_addc_u32 s64, s64, 0
	s_cmp_gt_u32 s65, 29
	s_cbranch_scc0 .LBB0_1056
	s_setprio 0
	s_and_b64 vcc, exec, s[22:23]
	s_cbranch_vccz .LBB0_1059
	s_barrier

;     __device__ __forceinline__ bool next(int i, Unit& u) const { if (i > 0 || c >= nitems) return false; u.pm = 64; u.pn = c % npn; u.k0 = (c / npn) * kslice; return true; }
; #define PG8_STAGE(bufoff, gbase, voff) do { _Pragma("unroll") for (int _i = 0; _i < 2; ++_i) \
;         __builtin_amdgcn_global_load_lds((const unsigned*)((const char*)(gbase) + (voff)[_i]), (PG8_LAS unsigned*)(lds + (bufoff) + ldsw + _i * 8192), 16, 0, 0); } while (0)
; #define PG8_LDA(dst, b, h) do { _Pragma("unroll") for (int m = 0; m < 4; ++m) _Pragma("unroll") for (int k = 0; k < 2; ++k) dst[m][k] = *(const PG8_LAS bf16x8*)(lds + PG8_SA(b, h) + aoff + m * 2048 + k * 1024); } while (0)
; #define PG8_LDB(dst, b, h) do { _Pragma("unroll") for (int n = 0; n < 2; ++n) _Pragma("unroll") for (int k = 0; k < 2; ++k) dst[n][k] = *(const PG8_LAS bf16x8*)(lds + PG8_SB(b, h) + boff + n * 2048 + k * 1024); } while (0)
; #define PG8_WAIT_V(n) asm volatile("s_waitcnt vmcnt(" #n ")" ::: "memory")
; template <class Epi, class Sched, bool ALIGN_EPI = false, bool SP2 = false>
; __device__ __forceinline__ void gemm_phase(PG8_LAS unsigned char* lds, const Gemm g, const Sched& S, const Epi& E) {
;     ...
;         const bool has_next = S.next(ui + 1, nxt);
;         const char* nA = has_next ? (const char*)g.A + (size_t)nxt.pm * tstep + (size_t)nxt.k0 * 2 : cA; const char* nB = has_next ? (const char*)g.Bt + (size_t)nxt.pn * tstep + (size_t)nxt.k0 * 2 : cB;
;         for (int t = 0; t < nt; t += 2) {
;             const bool last = (t == nt - 2);
;             const char* a1 = cA + (size_t)(t + 1) * kstep;
;             const char* a2 = last ? nA : cA + (size_t)(t + 2) * kstep; const char* b2 = last ? nB : cB + (size_t)(t + 2) * kstep;
;             const char* a3 = a2 + kstep; const char* b3 = b2 + kstep;
;             if (last && has_next) S.a_ready(nxt);
;             if constexpr (SP2) {
;             PG8_LDB(B0, 0, 0); PG8_LDB(B1, 0, 1); PG8_SCHED; PG8_LDA(At, 0, 0); PG8_STAGE(PG8_SA(1, 1), a1 + hstep, voffA);
;             PG8_WAIT_V(8); PG8_WAIT_L(0); PG8_BAR; PG8_MMA(0, 0, At, B0); PG8_MMA(0, 1, At, B1); PG8_BAR; PG8_SCHED;
;             PG8_LDA(At, 0, 1); PG8_STAGE(PG8_SB(0, 0), b2, voffB); PG8_STAGE(PG8_SB(0, 1), b2 + hstep, voffB); PG8_STAGE(PG8_SA(0, 0), a2, voffA);
;             PG8_WAIT_V(8); PG8_WAIT_L(0); PG8_BAR; PG8_MMA(1, 0, At, B0); PG8_MMA(1, 1, At, B1); PG8_BAR; PG8_SCHED;
.Lsp_skip_2:
.LBB0_1279:
	ds_read_b128 v[166:169], v149
	ds_read_b128 v[170:173], v149 offset:1024
	ds_read_b128 v[174:177], v149 offset:2048
	ds_read_b128 v[186:189], v149 offset:3072
	ds_read_b128 v[190:193], v159
	ds_read_b128 v[194:197], v159 offset:1024
	ds_read_b128 v[198:201], v159 offset:2048
	ds_read_b128 v[202:205], v159 offset:3072
	s_add_u32 s28, s26, 0xfff80080
	s_addc_u32 s29, s27, -1
	s_cmp_eq_u32 s54, 28
	s_cselect_b32 s31, s21, s29
	s_cselect_b32 s30, s50, s28
	s_cselect_b32 s29, s19, s53
	s_cselect_b32 s28, s51, s52
	s_add_i32 m0, s37, 0xc000
	ds_read_b128 v[206:209], v162
	ds_read_b128 v[210:213], v162 offset:1024
	ds_read_b128 v[214:217], v162 offset:2048
	ds_read_b128 v[218:221], v162 offset:3072
	ds_read_b128 v[222:225], v162 offset:4096
	ds_read_b128 v[226:229], v162 offset:5120
	ds_read_b128 v[230:233], v162 offset:6144
	ds_read_b128 v[234:237], v162 offset:7168
	global_load_lds_dwordx4 v128, s[26:27]
	s_add_i32 m0, s37, 0xe000
	s_nop 0
	global_load_lds_dwordx4 v130, s[26:27]
	s_waitcnt vmcnt(8)
	s_waitcnt lgkmcnt(0)
	s_barrier
	v_mfma_f32_16x16x32_bf16 v[124:127], v[166:169], v[206:209], v[124:127]
	v_mfma_f32_16x16x32_bf16 v[124:127], v[170:173], v[210:213], v[124:127]
	v_mfma_f32_16x16x32_bf16 v[120:123], v[186:189], v[210:213], v[120:123]
	v_mfma_f32_16x16x32_bf16 v[120:123], v[174:177], v[206:209], v[120:123]
	v_mfma_f32_16x16x32_bf16 v[104:107], v[174:177], v[214:217], v[104:107]
	v_mfma_f32_16x16x32_bf16 v[104:107], v[186:189], v[218:221], v[104:107]
	v_mfma_f32_16x16x32_bf16 v[108:111], v[170:173], v[218:221], v[108:111]
	v_mfma_f32_16x16x32_bf16 v[108:111], v[166:169], v[214:217], v[108:111]
	v_mfma_f32_16x16x32_bf16 v[92:95], v[166:169], v[222:225], v[92:95]
	v_mfma_f32_16x16x32_bf16 v[92:95], v[170:173], v[226:229], v[92:95]
	v_mfma_f32_16x16x32_bf16 v[88:91], v[186:189], v[226:229], v[88:91]
	v_mfma_f32_16x16x32_bf16 v[88:91], v[174:177], v[222:225], v[88:91]
	v_mfma_f32_16x16x32_bf16 v[72:75], v[174:177], v[230:233], v[72:75]
	v_mfma_f32_16x16x32_bf16 v[72:75], v[186:189], v[234:237], v[72:75]
	v_mfma_f32_16x16x32_bf16 v[76:79], v[170:173], v[234:237], v[76:79]
	v_mfma_f32_16x16x32_bf16 v[76:79], v[166:169], v[230:233], v[76:79]
	v_mfma_f32_16x16x32_bf16 v[116:119], v[190:193], v[206:209], v[116:119]
	v_mfma_f32_16x16x32_bf16 v[116:119], v[194:197], v[210:213], v[116:119]
	v_mfma_f32_16x16x32_bf16 v[112:115], v[202:205], v[210:213], v[112:115]
	v_mfma_f32_16x16x32_bf16 v[112:115], v[198:201], v[206:209], v[112:115]
	v_mfma_f32_16x16x32_bf16 v[96:99], v[198:201], v[214:217], v[96:99]
	v_mfma_f32_16x16x32_bf16 v[96:99], v[202:205], v[218:221], v[96:99]
	v_mfma_f32_16x16x32_bf16 v[100:103], v[194:197], v[218:221], v[100:103]
	v_mfma_f32_16x16x32_bf16 v[100:103], v[190:193], v[214:217], v[100:103]
	v_mfma_f32_16x16x32_bf16 v[84:87], v[190:193], v[222:225], v[84:87]
	v_mfma_f32_16x16x32_bf16 v[84:87], v[194:197], v[226:229], v[84:87]
	v_mfma_f32_16x16x32_bf16 v[80:83], v[202:205], v[226:229], v[80:83]
	v_mfma_f32_16x16x32_bf16 v[80:83], v[198:201], v[222:225], v[80:83]
	v_mfma_f32_16x16x32_bf16 v[64:67], v[198:201], v[230:233], v[64:67]
	v_mfma_f32_16x16x32_bf16 v[64:67], v[202:205], v[234:237], v[64:67]
	v_mfma_f32_16x16x32_bf16 v[68:71], v[194:197], v[234:237], v[68:71]
	v_mfma_f32_16x16x32_bf16 v[68:71], v[190:193], v[230:233], v[68:71]
	s_barrier
	s_add_u32 s98, s28, 0x80
	s_addc_u32 s99, s29, 0
	s_add_u32 s100, s30, 0x80
	s_addc_u32 s101, s31, 0
	s_add_i32 s55, s46, s36
	s_mov_b32 m0, s55
	ds_read_b128 v[206:209], v162 offset:16384
	ds_read_b128 v[210:213], v162 offset:17408
	ds_read_b128 v[214:217], v162 offset:18432
	ds_read_b128 v[218:221], v162 offset:19456
	ds_read_b128 v[222:225], v162 offset:20480
	ds_read_b128 v[226:229], v162 offset:21504
	ds_read_b128 v[230:233], v162 offset:22528
	ds_read_b128 v[234:237], v162 offset:23552
	global_load_lds_dwordx4 v152, s[28:29]
	s_add_i32 m0, s55, 0x2000
	s_add_u32 s56, s28, 0x80000
	s_addc_u32 s57, s29, 0
	s_add_i32 s55, s47, s36
	global_load_lds_dwordx4 v156, s[28:29]
	s_mov_b32 m0, s55
	s_nop 0
	global_load_lds_dwordx4 v152, s[56:57]
	s_add_i32 m0, s55, 0x2000
	s_nop 0
	global_load_lds_dwordx4 v156, s[56:57]
	s_mov_b32 m0, s37
	s_nop 0
	global_load_lds_dwordx4 v150, s[30:31]
	s_mov_b32 m0, s38
	s_nop 0
	global_load_lds_dwordx4 v154, s[30:31]
	s_waitcnt vmcnt(8)
	s_waitcnt lgkmcnt(0)
	s_barrier
	v_mfma_f32_16x16x32_bf16 v[60:63], v[166:169], v[206:209], v[60:63]
	v_mfma_f32_16x16x32_bf16 v[60:63], v[170:173], v[210:213], v[60:63]
	v_mfma_f32_16x16x32_bf16 v[56:59], v[186:189], v[210:213], v[56:59]
	v_mfma_f32_16x16x32_bf16 v[56:59], v[174:177], v[206:209], v[56:59]
	v_mfma_f32_16x16x32_bf16 v[40:43], v[174:177], v[214:217], v[40:43]
	v_mfma_f32_16x16x32_bf16 v[40:43], v[186:189], v[218:221], v[40:43]
	v_mfma_f32_16x16x32_bf16 v[44:47], v[170:173], v[218:221], v[44:47]
	v_mfma_f32_16x16x32_bf16 v[44:47], v[166:169], v[214:217], v[44:47]
	v_mfma_f32_16x16x32_bf16 v[28:31], v[166:169], v[222:225], v[28:31]
	v_mfma_f32_16x16x32_bf16 v[28:31], v[170:173], v[226:229], v[28:31]
	v_mfma_f32_16x16x32_bf16 v[24:27], v[186:189], v[226:229], v[24:27]
	v_mfma_f32_16x16x32_bf16 v[24:27], v[174:177], v[222:225], v[24:27]
	v_mfma_f32_16x16x32_bf16 v[8:11], v[174:177], v[230:233], v[8:11]
	v_mfma_f32_16x16x32_bf16 v[8:11], v[186:189], v[234:237], v[8:11]
	v_mfma_f32_16x16x32_bf16 v[12:15], v[170:173], v[234:237], v[12:15]
	v_mfma_f32_16x16x32_bf16 v[12:15], v[166:169], v[230:233], v[12:15]
	v_mfma_f32_16x16x32_bf16 v[52:55], v[190:193], v[206:209], v[52:55]
	v_mfma_f32_16x16x32_bf16 v[52:55], v[194:197], v[210:213], v[52:55]
	v_mfma_f32_16x16x32_bf16 v[48:51], v[202:205], v[210:213], v[48:51]
	v_mfma_f32_16x16x32_bf16 v[48:51], v[198:201], v[206:209], v[48:51]
	v_mfma_f32_16x16x32_bf16 v[32:35], v[198:201], v[214:217], v[32:35]
	v_mfma_f32_16x16x32_bf16 v[32:35], v[202:205], v[218:221], v[32:35]
	v_mfma_f32_16x16x32_bf16 v[36:39], v[194:197], v[218:221], v[36:39]
	v_mfma_f32_16x16x32_bf16 v[36:39], v[190:193], v[214:217], v[36:39]
	v_mfma_f32_16x16x32_bf16 v[20:23], v[190:193], v[222:225], v[20:23]
	v_mfma_f32_16x16x32_bf16 v[20:23], v[194:197], v[226:229], v[20:23]
	v_mfma_f32_16x16x32_bf16 v[16:19], v[202:205], v[226:229], v[16:19]
	v_mfma_f32_16x16x32_bf16 v[16:19], v[198:201], v[222:225], v[16:19]
	v_mfma_f32_16x16x32_bf16 v[0:3], v[198:201], v[230:233], v[0:3]
	v_mfma_f32_16x16x32_bf16 v[0:3], v[202:205], v[234:237], v[0:3]
	v_mfma_f32_16x16x32_bf16 v[4:7], v[194:197], v[234:237], v[4:7]
	v_mfma_f32_16x16x32_bf16 v[4:7], v[190:193], v[230:233], v[4:7]
	s_barrier
; #define PG8_STAGE(bufoff, gbase, voff) do { _Pragma("unroll") for (int _i = 0; _i < 2; ++_i) \
;         __builtin_amdgcn_global_load_lds((const unsigned*)((const char*)(gbase) + (voff)[_i]), (PG8_LAS unsigned*)(lds + (bufoff) + ldsw + _i * 8192), 16, 0, 0); } while (0)
; #define PG8_LDA(dst, b, h) do { _Pragma("unroll") for (int m = 0; m < 4; ++m) _Pragma("unroll") for (int k = 0; k < 2; ++k) dst[m][k] = *(const PG8_LAS bf16x8*)(lds + PG8_SA(b, h) + aoff + m * 2048 + k * 1024); } while (0)
; #define PG8_LDB(dst, b, h) do { _Pragma("unroll") for (int n = 0; n < 2; ++n) _Pragma("unroll") for (int k = 0; k < 2; ++k) dst[n][k] = *(const PG8_LAS bf16x8*)(lds + PG8_SB(b, h) + boff + n * 2048 + k * 1024); } while (0)
; #define PG8_MMA(ai, bj, At, Bt) do { __builtin_amdgcn_s_setprio(1); _Pragma("unroll") for (int m = 0; m < 4; ++m) _Pragma("unroll") for (int n = 0; n < 2; ++n) _Pragma("unroll") for (int k = 0; k < 2; ++k) \
;         acc[ai][bj][m][n] = __builtin_amdgcn_mfma_f32_16x16x32_bf16(Bt[n][k], At[m][k], acc[ai][bj][m][n], 0, 0, 0); __builtin_amdgcn_s_setprio(0); } while (0)
; #define PG8_WAIT_V(n) asm volatile("s_waitcnt vmcnt(" #n ")" ::: "memory")
; #define PG8_WAIT_L(n) asm volatile("s_waitcnt lgkmcnt(" #n ")" ::: "memory")
; #define PG8_BAR __builtin_amdgcn_s_barrier()
; #define PG8_SCHED __builtin_amdgcn_sched_barrier(0)
; template <class Epi, class Sched, bool ALIGN_EPI = false, bool SP2 = false>
; __device__ __forceinline__ void gemm_phase(PG8_LAS unsigned char* lds, const Gemm g, const Sched& S, const Epi& E) {
;     ...
;             PG8_LDB(B0, 1, 0); PG8_LDB(B1, 1, 1); PG8_SCHED; PG8_LDA(At, 1, 0); PG8_STAGE(PG8_SA(0, 1), a2 + hstep, voffA);
;             PG8_WAIT_V(8); PG8_WAIT_L(0); PG8_BAR; PG8_MMA(0, 0, At, B0); PG8_MMA(0, 1, At, B1); PG8_BAR; PG8_SCHED;
;             PG8_LDA(At, 1, 1); PG8_STAGE(PG8_SB(1, 0), b3, voffB); PG8_STAGE(PG8_SB(1, 1), b3 + hstep, voffB); PG8_STAGE(PG8_SA(1, 0), a3, voffA);
;             PG8_WAIT_V(8); PG8_WAIT_L(0); PG8_BAR; PG8_MMA(1, 0, At, B0); PG8_MMA(1, 1, At, B1); PG8_BAR; PG8_SCHED;
	s_add_i32 s55, 0, 0x18000
	v_add_u32_e32 v165, s55, v145
	s_add_i32 s56, 0, 0x1c000
	ds_read_b128 v[166:169], v165
	ds_read_b128 v[170:173], v165 offset:1024
	ds_read_b128 v[174:177], v165 offset:2048
	ds_read_b128 v[186:189], v165 offset:3072
	v_add_u32_e32 v165, s56, v145
	ds_read_b128 v[190:193], v165
	ds_read_b128 v[194:197], v165 offset:1024
	ds_read_b128 v[198:201], v165 offset:2048
	ds_read_b128 v[202:205], v165 offset:3072
	s_add_u32 s30, s30, 0x80000
	s_addc_u32 s31, s31, 0
	s_mov_b32 m0, s39
	ds_read_b128 v[206:209], v162 offset:32768
	ds_read_b128 v[210:213], v162 offset:33792
	ds_read_b128 v[214:217], v162 offset:34816
	ds_read_b128 v[218:221], v162 offset:35840
	ds_read_b128 v[222:225], v162 offset:36864
	ds_read_b128 v[226:229], v162 offset:37888
	ds_read_b128 v[230:233], v162 offset:38912
	ds_read_b128 v[234:237], v162 offset:39936
	global_load_lds_dwordx4 v150, s[30:31]
	s_mov_b32 m0, s40
	s_nop 0
	global_load_lds_dwordx4 v154, s[30:31]
	s_waitcnt vmcnt(8)
	s_waitcnt lgkmcnt(0)
	s_barrier
	v_mfma_f32_16x16x32_bf16 v[124:127], v[166:169], v[206:209], v[124:127]
	v_mfma_f32_16x16x32_bf16 v[124:127], v[170:173], v[210:213], v[124:127]
	v_mfma_f32_16x16x32_bf16 v[120:123], v[186:189], v[210:213], v[120:123]
	v_mfma_f32_16x16x32_bf16 v[120:123], v[174:177], v[206:209], v[120:123]
	v_mfma_f32_16x16x32_bf16 v[104:107], v[174:177], v[214:217], v[104:107]
	v_mfma_f32_16x16x32_bf16 v[104:107], v[186:189], v[218:221], v[104:107]
	v_mfma_f32_16x16x32_bf16 v[108:111], v[170:173], v[218:221], v[108:111]
	v_mfma_f32_16x16x32_bf16 v[108:111], v[166:169], v[214:217], v[108:111]
	v_mfma_f32_16x16x32_bf16 v[92:95], v[166:169], v[222:225], v[92:95]
	v_mfma_f32_16x16x32_bf16 v[92:95], v[170:173], v[226:229], v[92:95]
	v_mfma_f32_16x16x32_bf16 v[88:91], v[186:189], v[226:229], v[88:91]
	v_mfma_f32_16x16x32_bf16 v[88:91], v[174:177], v[222:225], v[88:91]
	v_mfma_f32_16x16x32_bf16 v[72:75], v[174:177], v[230:233], v[72:75]
	v_mfma_f32_16x16x32_bf16 v[72:75], v[186:189], v[234:237], v[72:75]
	v_mfma_f32_16x16x32_bf16 v[76:79], v[170:173], v[234:237], v[76:79]
	v_mfma_f32_16x16x32_bf16 v[76:79], v[166:169], v[230:233], v[76:79]
	v_mfma_f32_16x16x32_bf16 v[116:119], v[190:193], v[206:209], v[116:119]
	v_mfma_f32_16x16x32_bf16 v[116:119], v[194:197], v[210:213], v[116:119]
	v_mfma_f32_16x16x32_bf16 v[112:115], v[202:205], v[210:213], v[112:115]
	v_mfma_f32_16x16x32_bf16 v[112:115], v[198:201], v[206:209], v[112:115]
	v_mfma_f32_16x16x32_bf16 v[96:99], v[198:201], v[214:217], v[96:99]
	v_mfma_f32_16x16x32_bf16 v[96:99], v[202:205], v[218:221], v[96:99]
	v_mfma_f32_16x16x32_bf16 v[100:103], v[194:197], v[218:221], v[100:103]
	v_mfma_f32_16x16x32_bf16 v[100:103], v[190:193], v[214:217], v[100:103]
	v_mfma_f32_16x16x32_bf16 v[84:87], v[190:193], v[222:225], v[84:87]
	v_mfma_f32_16x16x32_bf16 v[84:87], v[194:197], v[226:229], v[84:87]
	v_mfma_f32_16x16x32_bf16 v[80:83], v[202:205], v[226:229], v[80:83]
	v_mfma_f32_16x16x32_bf16 v[80:83], v[198:201], v[222:225], v[80:83]
	v_mfma_f32_16x16x32_bf16 v[64:67], v[198:201], v[230:233], v[64:67]
	v_mfma_f32_16x16x32_bf16 v[64:67], v[202:205], v[234:237], v[64:67]
	v_mfma_f32_16x16x32_bf16 v[68:71], v[194:197], v[234:237], v[68:71]
	v_mfma_f32_16x16x32_bf16 v[68:71], v[190:193], v[230:233], v[68:71]
	s_barrier
	s_add_i32 s30, s55, s36
	s_mov_b32 m0, s30
	ds_read_b128 v[206:209], v162 offset:49152
	ds_read_b128 v[210:213], v162 offset:50176
	ds_read_b128 v[214:217], v162 offset:51200
	ds_read_b128 v[218:221], v162 offset:52224
	ds_read_b128 v[222:225], v162 offset:53248
	ds_read_b128 v[226:229], v162 offset:54272
	ds_read_b128 v[230:233], v162 offset:55296
	ds_read_b128 v[234:237], v162 offset:56320
	global_load_lds_dwordx4 v152, s[98:99]
	s_add_i32 m0, s30, 0x2000
	s_add_u32 s28, s28, 0x80080
	s_addc_u32 s29, s29, 0
	s_add_i32 s30, s56, s36
	global_load_lds_dwordx4 v156, s[98:99]
	s_mov_b32 m0, s30
	s_nop 0
	global_load_lds_dwordx4 v152, s[28:29]
	s_add_i32 m0, s30, 0x2000
	s_nop 0
	global_load_lds_dwordx4 v156, s[28:29]
	s_mov_b32 m0, s42
	s_nop 0
	global_load_lds_dwordx4 v150, s[100:101]
	s_mov_b32 m0, s43
	s_nop 0
	global_load_lds_dwordx4 v154, s[100:101]
	s_waitcnt vmcnt(8)
	s_waitcnt lgkmcnt(0)
	s_barrier
	v_mfma_f32_16x16x32_bf16 v[60:63], v[166:169], v[206:209], v[60:63]
	v_mfma_f32_16x16x32_bf16 v[60:63], v[170:173], v[210:213], v[60:63]
	v_mfma_f32_16x16x32_bf16 v[56:59], v[186:189], v[210:213], v[56:59]
	v_mfma_f32_16x16x32_bf16 v[56:59], v[174:177], v[206:209], v[56:59]
	v_mfma_f32_16x16x32_bf16 v[40:43], v[174:177], v[214:217], v[40:43]
	v_mfma_f32_16x16x32_bf16 v[40:43], v[186:189], v[218:221], v[40:43]
	v_mfma_f32_16x16x32_bf16 v[44:47], v[170:173], v[218:221], v[44:47]
	v_mfma_f32_16x16x32_bf16 v[44:47], v[166:169], v[214:217], v[44:47]
	v_mfma_f32_16x16x32_bf16 v[28:31], v[166:169], v[222:225], v[28:31]
	v_mfma_f32_16x16x32_bf16 v[28:31], v[170:173], v[226:229], v[28:31]
	v_mfma_f32_16x16x32_bf16 v[24:27], v[186:189], v[226:229], v[24:27]
	v_mfma_f32_16x16x32_bf16 v[24:27], v[174:177], v[222:225], v[24:27]
	v_mfma_f32_16x16x32_bf16 v[8:11], v[174:177], v[230:233], v[8:11]
	v_mfma_f32_16x16x32_bf16 v[8:11], v[186:189], v[234:237], v[8:11]
	v_mfma_f32_16x16x32_bf16 v[12:15], v[170:173], v[234:237], v[12:15]
	v_mfma_f32_16x16x32_bf16 v[12:15], v[166:169], v[230:233], v[12:15]
	v_mfma_f32_16x16x32_bf16 v[52:55], v[190:193], v[206:209], v[52:55]
	v_mfma_f32_16x16x32_bf16 v[52:55], v[194:197], v[210:213], v[52:55]
	v_mfma_f32_16x16x32_bf16 v[48:51], v[202:205], v[210:213], v[48:51]
	v_mfma_f32_16x16x32_bf16 v[48:51], v[198:201], v[206:209], v[48:51]
	v_mfma_f32_16x16x32_bf16 v[32:35], v[198:201], v[214:217], v[32:35]
	v_mfma_f32_16x16x32_bf16 v[32:35], v[202:205], v[218:221], v[32:35]
	v_mfma_f32_16x16x32_bf16 v[36:39], v[194:197], v[218:221], v[36:39]
	v_mfma_f32_16x16x32_bf16 v[36:39], v[190:193], v[214:217], v[36:39]
	v_mfma_f32_16x16x32_bf16 v[20:23], v[190:193], v[222:225], v[20:23]
	v_mfma_f32_16x16x32_bf16 v[20:23], v[194:197], v[226:229], v[20:23]
	v_mfma_f32_16x16x32_bf16 v[16:19], v[202:205], v[226:229], v[16:19]
	v_mfma_f32_16x16x32_bf16 v[16:19], v[198:201], v[222:225], v[16:19]
	v_mfma_f32_16x16x32_bf16 v[0:3], v[198:201], v[230:233], v[0:3]
	v_mfma_f32_16x16x32_bf16 v[0:3], v[202:205], v[234:237], v[0:3]
	v_mfma_f32_16x16x32_bf16 v[4:7], v[194:197], v[234:237], v[4:7]
	v_mfma_f32_16x16x32_bf16 v[4:7], v[190:193], v[230:233], v[4:7]
	s_barrier
	s_add_i32 s54, s54, 2
	s_add_u32 s26, s26, 0x100
	s_addc_u32 s27, s27, 0
	s_add_u32 s52, s52, 0x100
	s_addc_u32 s53, s53, 0
	s_cmp_gt_u32 s54, 29
	s_cbranch_scc0 .LBB0_1279
	s_setprio 0
	s_and_b64 vcc, exec, s[16:17]
	s_cbranch_vccz .LBB0_1282
	s_barrier

;     __device__ __forceinline__ bool next(int i, Unit& u) const { if (i > 0 || c >= nitems) return false; u.pm = 64; u.pn = c % npn; u.k0 = (c / npn) * kslice; return true; }
; #define PG8_STAGE(bufoff, gbase, voff) do { _Pragma("unroll") for (int _i = 0; _i < 2; ++_i) \
;         __builtin_amdgcn_global_load_lds((const unsigned*)((const char*)(gbase) + (voff)[_i]), (PG8_LAS unsigned*)(lds + (bufoff) + ldsw + _i * 8192), 16, 0, 0); } while (0)
; #define PG8_LDA(dst, b, h) do { _Pragma("unroll") for (int m = 0; m < 4; ++m) _Pragma("unroll") for (int k = 0; k < 2; ++k) dst[m][k] = *(const PG8_LAS bf16x8*)(lds + PG8_SA(b, h) + aoff + m * 2048 + k * 1024); } while (0)
; #define PG8_LDB(dst, b, h) do { _Pragma("unroll") for (int n = 0; n < 2; ++n) _Pragma("unroll") for (int k = 0; k < 2; ++k) dst[n][k] = *(const PG8_LAS bf16x8*)(lds + PG8_SB(b, h) + boff + n * 2048 + k * 1024); } while (0)
; #define PG8_WAIT_V(n) asm volatile("s_waitcnt vmcnt(" #n ")" ::: "memory")
; template <class Epi, class Sched, bool ALIGN_EPI = false, bool SP2 = false>
; __device__ __forceinline__ void gemm_phase(PG8_LAS unsigned char* lds, const Gemm g, const Sched& S, const Epi& E) {
;     ...
;         const bool has_next = S.next(ui + 1, nxt);
;         const char* nA = has_next ? (const char*)g.A + (size_t)nxt.pm * tstep + (size_t)nxt.k0 * 2 : cA; const char* nB = has_next ? (const char*)g.Bt + (size_t)nxt.pn * tstep + (size_t)nxt.k0 * 2 : cB;
;         for (int t = 0; t < nt; t += 2) {
;             const bool last = (t == nt - 2);
;             const char* a1 = cA + (size_t)(t + 1) * kstep;
;             const char* a2 = last ? nA : cA + (size_t)(t + 2) * kstep; const char* b2 = last ? nB : cB + (size_t)(t + 2) * kstep;
;             const char* a3 = a2 + kstep; const char* b3 = b2 + kstep;
;             if (last && has_next) S.a_ready(nxt);
;             if constexpr (SP2) {
;             PG8_LDB(B0, 0, 0); PG8_LDB(B1, 0, 1); PG8_SCHED; PG8_LDA(At, 0, 0); PG8_STAGE(PG8_SA(1, 1), a1 + hstep, voffA);
;             PG8_WAIT_V(8); PG8_WAIT_L(0); PG8_BAR; PG8_MMA(0, 0, At, B0); PG8_MMA(0, 1, At, B1); PG8_BAR; PG8_SCHED;
;             PG8_LDA(At, 0, 1); PG8_STAGE(PG8_SB(0, 0), b2, voffB); PG8_STAGE(PG8_SB(0, 1), b2 + hstep, voffB); PG8_STAGE(PG8_SA(0, 0), a2, voffA);
;             PG8_WAIT_V(8); PG8_WAIT_L(0); PG8_BAR; PG8_MMA(1, 0, At, B0); PG8_MMA(1, 1, At, B1); PG8_BAR; PG8_SCHED;
.Lsp_skip_1:
.LBB0_1361:
	ds_read_b128 v[128:131], v166
	ds_read_b128 v[132:135], v166 offset:1024
	ds_read_b128 v[160:163], v166 offset:2048
	ds_read_b128 v[170:173], v166 offset:3072
	ds_read_b128 v[174:177], v167
	ds_read_b128 v[186:189], v167 offset:1024
	ds_read_b128 v[190:193], v167 offset:2048
	ds_read_b128 v[194:197], v167 offset:3072
	s_add_u32 s22, s20, 0xffea0080
	s_addc_u32 s23, s21, -1
	s_cmpk_eq_i32 s55, 0x54
	s_cselect_b32 s25, s7, s23
	s_cselect_b32 s24, s6, s22
	s_cselect_b32 s23, s19, s54
	s_cselect_b32 s22, s18, s53
	s_add_i32 m0, s29, 0xc000
	ds_read_b128 v[198:201], v168
	ds_read_b128 v[202:205], v168 offset:1024
	ds_read_b128 v[206:209], v168 offset:2048
	ds_read_b128 v[210:213], v168 offset:3072
	ds_read_b128 v[214:217], v168 offset:4096
	ds_read_b128 v[218:221], v168 offset:5120
	ds_read_b128 v[222:225], v168 offset:6144
	ds_read_b128 v[226:229], v168 offset:7168
	global_load_lds_dwordx4 v150, s[20:21]
	s_add_i32 m0, s29, 0xe000
	s_nop 0
	global_load_lds_dwordx4 v152, s[20:21]
	s_waitcnt vmcnt(8)
	s_waitcnt lgkmcnt(0)
	s_barrier
	v_mfma_f32_16x16x32_bf16 v[124:127], v[128:131], v[198:201], v[124:127]
	v_mfma_f32_16x16x32_bf16 v[124:127], v[132:135], v[202:205], v[124:127]
	v_mfma_f32_16x16x32_bf16 v[120:123], v[170:173], v[202:205], v[120:123]
	v_mfma_f32_16x16x32_bf16 v[120:123], v[160:163], v[198:201], v[120:123]
	v_mfma_f32_16x16x32_bf16 v[104:107], v[160:163], v[206:209], v[104:107]
	v_mfma_f32_16x16x32_bf16 v[104:107], v[170:173], v[210:213], v[104:107]
	v_mfma_f32_16x16x32_bf16 v[108:111], v[132:135], v[210:213], v[108:111]
	v_mfma_f32_16x16x32_bf16 v[108:111], v[128:131], v[206:209], v[108:111]
	v_mfma_f32_16x16x32_bf16 v[92:95], v[128:131], v[214:217], v[92:95]
	v_mfma_f32_16x16x32_bf16 v[92:95], v[132:135], v[218:221], v[92:95]
	v_mfma_f32_16x16x32_bf16 v[88:91], v[170:173], v[218:221], v[88:91]
	v_mfma_f32_16x16x32_bf16 v[88:91], v[160:163], v[214:217], v[88:91]
	v_mfma_f32_16x16x32_bf16 v[72:75], v[160:163], v[222:225], v[72:75]
	v_mfma_f32_16x16x32_bf16 v[72:75], v[170:173], v[226:229], v[72:75]
	v_mfma_f32_16x16x32_bf16 v[76:79], v[132:135], v[226:229], v[76:79]
	v_mfma_f32_16x16x32_bf16 v[76:79], v[128:131], v[222:225], v[76:79]
	v_mfma_f32_16x16x32_bf16 v[116:119], v[174:177], v[198:201], v[116:119]
	v_mfma_f32_16x16x32_bf16 v[116:119], v[186:189], v[202:205], v[116:119]
	v_mfma_f32_16x16x32_bf16 v[112:115], v[194:197], v[202:205], v[112:115]
	v_mfma_f32_16x16x32_bf16 v[112:115], v[190:193], v[198:201], v[112:115]
	v_mfma_f32_16x16x32_bf16 v[96:99], v[190:193], v[206:209], v[96:99]
	v_mfma_f32_16x16x32_bf16 v[96:99], v[194:197], v[210:213], v[96:99]
	v_mfma_f32_16x16x32_bf16 v[100:103], v[186:189], v[210:213], v[100:103]
	v_mfma_f32_16x16x32_bf16 v[100:103], v[174:177], v[206:209], v[100:103]
	v_mfma_f32_16x16x32_bf16 v[84:87], v[174:177], v[214:217], v[84:87]
	v_mfma_f32_16x16x32_bf16 v[84:87], v[186:189], v[218:221], v[84:87]
	v_mfma_f32_16x16x32_bf16 v[80:83], v[194:197], v[218:221], v[80:83]
	v_mfma_f32_16x16x32_bf16 v[80:83], v[190:193], v[214:217], v[80:83]
	v_mfma_f32_16x16x32_bf16 v[64:67], v[190:193], v[222:225], v[64:67]
	v_mfma_f32_16x16x32_bf16 v[64:67], v[194:197], v[226:229], v[64:67]
	v_mfma_f32_16x16x32_bf16 v[68:71], v[186:189], v[226:229], v[68:71]
	v_mfma_f32_16x16x32_bf16 v[68:71], v[174:177], v[222:225], v[68:71]
	s_barrier
	s_add_u32 s98, s22, 0x80
	s_addc_u32 s99, s23, 0
	s_add_u32 s100, s24, 0x80
	s_addc_u32 s101, s25, 0
	s_add_i32 s56, s43, s28
	s_mov_b32 m0, s56
	ds_read_b128 v[198:201], v168 offset:16384
	ds_read_b128 v[202:205], v168 offset:17408
	ds_read_b128 v[206:209], v168 offset:18432
	ds_read_b128 v[210:213], v168 offset:19456
	ds_read_b128 v[214:217], v168 offset:20480
	ds_read_b128 v[218:221], v168 offset:21504
	ds_read_b128 v[222:225], v168 offset:22528
	ds_read_b128 v[226:229], v168 offset:23552
	global_load_lds_dwordx4 v144, s[22:23]
	s_add_i32 m0, s56, 0x2000
	s_add_u32 s56, s22, 0x160000
	s_addc_u32 s57, s23, 0
	s_add_i32 s58, s44, s28
	global_load_lds_dwordx4 v148, s[22:23]
	s_mov_b32 m0, s58
	s_nop 0
	global_load_lds_dwordx4 v144, s[56:57]
	s_add_i32 m0, s58, 0x2000
	s_nop 0
	global_load_lds_dwordx4 v148, s[56:57]
	s_mov_b32 m0, s29
	s_nop 0
	global_load_lds_dwordx4 v142, s[24:25]
	s_mov_b32 m0, s30
	s_nop 0
	global_load_lds_dwordx4 v146, s[24:25]
	s_waitcnt vmcnt(8)
	s_waitcnt lgkmcnt(0)
	s_barrier
	v_mfma_f32_16x16x32_bf16 v[60:63], v[128:131], v[198:201], v[60:63]
	v_mfma_f32_16x16x32_bf16 v[60:63], v[132:135], v[202:205], v[60:63]
	v_mfma_f32_16x16x32_bf16 v[56:59], v[170:173], v[202:205], v[56:59]
	v_mfma_f32_16x16x32_bf16 v[56:59], v[160:163], v[198:201], v[56:59]
	v_mfma_f32_16x16x32_bf16 v[40:43], v[160:163], v[206:209], v[40:43]
	v_mfma_f32_16x16x32_bf16 v[40:43], v[170:173], v[210:213], v[40:43]
	v_mfma_f32_16x16x32_bf16 v[44:47], v[132:135], v[210:213], v[44:47]
	v_mfma_f32_16x16x32_bf16 v[44:47], v[128:131], v[206:209], v[44:47]
	v_mfma_f32_16x16x32_bf16 v[28:31], v[128:131], v[214:217], v[28:31]
	v_mfma_f32_16x16x32_bf16 v[28:31], v[132:135], v[218:221], v[28:31]
	v_mfma_f32_16x16x32_bf16 v[24:27], v[170:173], v[218:221], v[24:27]
	v_mfma_f32_16x16x32_bf16 v[24:27], v[160:163], v[214:217], v[24:27]
	v_mfma_f32_16x16x32_bf16 v[8:11], v[160:163], v[222:225], v[8:11]
	v_mfma_f32_16x16x32_bf16 v[8:11], v[170:173], v[226:229], v[8:11]
	v_mfma_f32_16x16x32_bf16 v[12:15], v[132:135], v[226:229], v[12:15]
	v_mfma_f32_16x16x32_bf16 v[12:15], v[128:131], v[222:225], v[12:15]
	v_mfma_f32_16x16x32_bf16 v[52:55], v[174:177], v[198:201], v[52:55]
	v_mfma_f32_16x16x32_bf16 v[52:55], v[186:189], v[202:205], v[52:55]
	v_mfma_f32_16x16x32_bf16 v[48:51], v[194:197], v[202:205], v[48:51]
	v_mfma_f32_16x16x32_bf16 v[48:51], v[190:193], v[198:201], v[48:51]
	v_mfma_f32_16x16x32_bf16 v[32:35], v[190:193], v[206:209], v[32:35]
	v_mfma_f32_16x16x32_bf16 v[32:35], v[194:197], v[210:213], v[32:35]
	v_mfma_f32_16x16x32_bf16 v[36:39], v[186:189], v[210:213], v[36:39]
	v_mfma_f32_16x16x32_bf16 v[36:39], v[174:177], v[206:209], v[36:39]
	v_mfma_f32_16x16x32_bf16 v[20:23], v[174:177], v[214:217], v[20:23]
	v_mfma_f32_16x16x32_bf16 v[20:23], v[186:189], v[218:221], v[20:23]
	v_mfma_f32_16x16x32_bf16 v[16:19], v[194:197], v[218:221], v[16:19]
	v_mfma_f32_16x16x32_bf16 v[16:19], v[190:193], v[214:217], v[16:19]
	v_mfma_f32_16x16x32_bf16 v[0:3], v[190:193], v[222:225], v[0:3]
	v_mfma_f32_16x16x32_bf16 v[0:3], v[194:197], v[226:229], v[0:3]
	v_mfma_f32_16x16x32_bf16 v[4:7], v[186:189], v[226:229], v[4:7]
	v_mfma_f32_16x16x32_bf16 v[4:7], v[174:177], v[222:225], v[4:7]
	s_barrier
; #define PG8_STAGE(bufoff, gbase, voff) do { _Pragma("unroll") for (int _i = 0; _i < 2; ++_i) \
;         __builtin_amdgcn_global_load_lds((const unsigned*)((const char*)(gbase) + (voff)[_i]), (PG8_LAS unsigned*)(lds + (bufoff) + ldsw + _i * 8192), 16, 0, 0); } while (0)
; #define PG8_LDA(dst, b, h) do { _Pragma("unroll") for (int m = 0; m < 4; ++m) _Pragma("unroll") for (int k = 0; k < 2; ++k) dst[m][k] = *(const PG8_LAS bf16x8*)(lds + PG8_SA(b, h) + aoff + m * 2048 + k * 1024); } while (0)
; #define PG8_LDB(dst, b, h) do { _Pragma("unroll") for (int n = 0; n < 2; ++n) _Pragma("unroll") for (int k = 0; k < 2; ++k) dst[n][k] = *(const PG8_LAS bf16x8*)(lds + PG8_SB(b, h) + boff + n * 2048 + k * 1024); } while (0)
; #define PG8_MMA(ai, bj, At, Bt) do { __builtin_amdgcn_s_setprio(1); _Pragma("unroll") for (int m = 0; m < 4; ++m) _Pragma("unroll") for (int n = 0; n < 2; ++n) _Pragma("unroll") for (int k = 0; k < 2; ++k) \
;         acc[ai][bj][m][n] = __builtin_amdgcn_mfma_f32_16x16x32_bf16(Bt[n][k], At[m][k], acc[ai][bj][m][n], 0, 0, 0); __builtin_amdgcn_s_setprio(0); } while (0)
; #define PG8_WAIT_V(n) asm volatile("s_waitcnt vmcnt(" #n ")" ::: "memory")
; #define PG8_WAIT_L(n) asm volatile("s_waitcnt lgkmcnt(" #n ")" ::: "memory")
; #define PG8_BAR __builtin_amdgcn_s_barrier()
; #define PG8_SCHED __builtin_amdgcn_sched_barrier(0)
; template <class Epi, class Sched, bool ALIGN_EPI = false, bool SP2 = false>
; __device__ __forceinline__ void gemm_phase(PG8_LAS unsigned char* lds, const Gemm g, const Sched& S, const Epi& E) {
;     ...
;             PG8_LDB(B0, 1, 0); PG8_LDB(B1, 1, 1); PG8_SCHED; PG8_LDA(At, 1, 0); PG8_STAGE(PG8_SA(0, 1), a2 + hstep, voffA);
;             PG8_WAIT_V(8); PG8_WAIT_L(0); PG8_BAR; PG8_MMA(0, 0, At, B0); PG8_MMA(0, 1, At, B1); PG8_BAR; PG8_SCHED;
;             PG8_LDA(At, 1, 1); PG8_STAGE(PG8_SB(1, 0), b3, voffB); PG8_STAGE(PG8_SB(1, 1), b3 + hstep, voffB); PG8_STAGE(PG8_SA(1, 0), a3, voffA);
;             PG8_WAIT_V(8); PG8_WAIT_L(0); PG8_BAR; PG8_MMA(1, 0, At, B0); PG8_MMA(1, 1, At, B1); PG8_BAR; PG8_SCHED;
	s_add_i32 s56, 0, 0x18000
	v_add_u32_e32 v169, s56, v164
	s_add_i32 s57, 0, 0x1c000
	ds_read_b128 v[128:131], v169
	ds_read_b128 v[132:135], v169 offset:1024
	ds_read_b128 v[160:163], v169 offset:2048
	ds_read_b128 v[170:173], v169 offset:3072
	v_add_u32_e32 v169, s57, v164
	ds_read_b128 v[174:177], v169
	ds_read_b128 v[186:189], v169 offset:1024
	ds_read_b128 v[190:193], v169 offset:2048
	ds_read_b128 v[194:197], v169 offset:3072
	s_add_u32 s24, s24, 0x160000
	s_addc_u32 s25, s25, 0
	s_mov_b32 m0, s31
	ds_read_b128 v[198:201], v168 offset:32768
	ds_read_b128 v[202:205], v168 offset:33792
	ds_read_b128 v[206:209], v168 offset:34816
	ds_read_b128 v[210:213], v168 offset:35840
	ds_read_b128 v[214:217], v168 offset:36864
	ds_read_b128 v[218:221], v168 offset:37888
	ds_read_b128 v[222:225], v168 offset:38912
	ds_read_b128 v[226:229], v168 offset:39936
	global_load_lds_dwordx4 v142, s[24:25]
	s_mov_b32 m0, s33
	s_nop 0
	global_load_lds_dwordx4 v146, s[24:25]
	s_waitcnt vmcnt(8)
	s_waitcnt lgkmcnt(0)
	s_barrier
	v_mfma_f32_16x16x32_bf16 v[124:127], v[128:131], v[198:201], v[124:127]
	v_mfma_f32_16x16x32_bf16 v[124:127], v[132:135], v[202:205], v[124:127]
	v_mfma_f32_16x16x32_bf16 v[120:123], v[170:173], v[202:205], v[120:123]
	v_mfma_f32_16x16x32_bf16 v[120:123], v[160:163], v[198:201], v[120:123]
	v_mfma_f32_16x16x32_bf16 v[104:107], v[160:163], v[206:209], v[104:107]
	v_mfma_f32_16x16x32_bf16 v[104:107], v[170:173], v[210:213], v[104:107]
	v_mfma_f32_16x16x32_bf16 v[108:111], v[132:135], v[210:213], v[108:111]
	v_mfma_f32_16x16x32_bf16 v[108:111], v[128:131], v[206:209], v[108:111]
	v_mfma_f32_16x16x32_bf16 v[92:95], v[128:131], v[214:217], v[92:95]
	v_mfma_f32_16x16x32_bf16 v[92:95], v[132:135], v[218:221], v[92:95]
	v_mfma_f32_16x16x32_bf16 v[88:91], v[170:173], v[218:221], v[88:91]
	v_mfma_f32_16x16x32_bf16 v[88:91], v[160:163], v[214:217], v[88:91]
	v_mfma_f32_16x16x32_bf16 v[72:75], v[160:163], v[222:225], v[72:75]
	v_mfma_f32_16x16x32_bf16 v[72:75], v[170:173], v[226:229], v[72:75]
	v_mfma_f32_16x16x32_bf16 v[76:79], v[132:135], v[226:229], v[76:79]
	v_mfma_f32_16x16x32_bf16 v[76:79], v[128:131], v[222:225], v[76:79]
	v_mfma_f32_16x16x32_bf16 v[116:119], v[174:177], v[198:201], v[116:119]
	v_mfma_f32_16x16x32_bf16 v[116:119], v[186:189], v[202:205], v[116:119]
	v_mfma_f32_16x16x32_bf16 v[112:115], v[194:197], v[202:205], v[112:115]
	v_mfma_f32_16x16x32_bf16 v[112:115], v[190:193], v[198:201], v[112:115]
	v_mfma_f32_16x16x32_bf16 v[96:99], v[190:193], v[206:209], v[96:99]
	v_mfma_f32_16x16x32_bf16 v[96:99], v[194:197], v[210:213], v[96:99]
	v_mfma_f32_16x16x32_bf16 v[100:103], v[186:189], v[210:213], v[100:103]
	v_mfma_f32_16x16x32_bf16 v[100:103], v[174:177], v[206:209], v[100:103]
	v_mfma_f32_16x16x32_bf16 v[84:87], v[174:177], v[214:217], v[84:87]
	v_mfma_f32_16x16x32_bf16 v[84:87], v[186:189], v[218:221], v[84:87]
	v_mfma_f32_16x16x32_bf16 v[80:83], v[194:197], v[218:221], v[80:83]
	v_mfma_f32_16x16x32_bf16 v[80:83], v[190:193], v[214:217], v[80:83]
	v_mfma_f32_16x16x32_bf16 v[64:67], v[190:193], v[222:225], v[64:67]
	v_mfma_f32_16x16x32_bf16 v[64:67], v[194:197], v[226:229], v[64:67]
	v_mfma_f32_16x16x32_bf16 v[68:71], v[186:189], v[226:229], v[68:71]
	v_mfma_f32_16x16x32_bf16 v[68:71], v[174:177], v[222:225], v[68:71]
	s_barrier
	s_add_i32 s24, s56, s28
	s_mov_b32 m0, s24
	ds_read_b128 v[198:201], v168 offset:49152
	ds_read_b128 v[202:205], v168 offset:50176
	ds_read_b128 v[206:209], v168 offset:51200
	ds_read_b128 v[210:213], v168 offset:52224
	ds_read_b128 v[214:217], v168 offset:53248
	ds_read_b128 v[218:221], v168 offset:54272
	ds_read_b128 v[222:225], v168 offset:55296
	ds_read_b128 v[226:229], v168 offset:56320
	global_load_lds_dwordx4 v144, s[98:99]
	s_add_i32 m0, s24, 0x2000
	s_add_u32 s22, s22, 0x160080
	s_addc_u32 s23, s23, 0
	s_add_i32 s24, s57, s28
	global_load_lds_dwordx4 v148, s[98:99]
	s_mov_b32 m0, s24
	s_nop 0
	global_load_lds_dwordx4 v144, s[22:23]
	s_add_i32 m0, s24, 0x2000
	s_nop 0
	global_load_lds_dwordx4 v148, s[22:23]
	s_mov_b32 m0, s38
	s_nop 0
	global_load_lds_dwordx4 v142, s[100:101]
	s_mov_b32 m0, s39
	s_nop 0
	global_load_lds_dwordx4 v146, s[100:101]
	s_waitcnt vmcnt(8)
	s_waitcnt lgkmcnt(0)
	s_barrier
	v_mfma_f32_16x16x32_bf16 v[60:63], v[128:131], v[198:201], v[60:63]
	v_mfma_f32_16x16x32_bf16 v[60:63], v[132:135], v[202:205], v[60:63]
	v_mfma_f32_16x16x32_bf16 v[56:59], v[170:173], v[202:205], v[56:59]
	v_mfma_f32_16x16x32_bf16 v[56:59], v[160:163], v[198:201], v[56:59]
	v_mfma_f32_16x16x32_bf16 v[40:43], v[160:163], v[206:209], v[40:43]
	v_mfma_f32_16x16x32_bf16 v[40:43], v[170:173], v[210:213], v[40:43]
	v_mfma_f32_16x16x32_bf16 v[44:47], v[132:135], v[210:213], v[44:47]
	v_mfma_f32_16x16x32_bf16 v[44:47], v[128:131], v[206:209], v[44:47]
	v_mfma_f32_16x16x32_bf16 v[28:31], v[128:131], v[214:217], v[28:31]
	v_mfma_f32_16x16x32_bf16 v[28:31], v[132:135], v[218:221], v[28:31]
	v_mfma_f32_16x16x32_bf16 v[24:27], v[170:173], v[218:221], v[24:27]
	v_mfma_f32_16x16x32_bf16 v[24:27], v[160:163], v[214:217], v[24:27]
	v_mfma_f32_16x16x32_bf16 v[8:11], v[160:163], v[222:225], v[8:11]
	v_mfma_f32_16x16x32_bf16 v[8:11], v[170:173], v[226:229], v[8:11]
	v_mfma_f32_16x16x32_bf16 v[12:15], v[132:135], v[226:229], v[12:15]
	v_mfma_f32_16x16x32_bf16 v[12:15], v[128:131], v[222:225], v[12:15]
	v_mfma_f32_16x16x32_bf16 v[52:55], v[174:177], v[198:201], v[52:55]
	v_mfma_f32_16x16x32_bf16 v[52:55], v[186:189], v[202:205], v[52:55]
	v_mfma_f32_16x16x32_bf16 v[48:51], v[194:197], v[202:205], v[48:51]
	v_mfma_f32_16x16x32_bf16 v[48:51], v[190:193], v[198:201], v[48:51]
	v_mfma_f32_16x16x32_bf16 v[32:35], v[190:193], v[206:209], v[32:35]
	v_mfma_f32_16x16x32_bf16 v[32:35], v[194:197], v[210:213], v[32:35]
	v_mfma_f32_16x16x32_bf16 v[36:39], v[186:189], v[210:213], v[36:39]
	v_mfma_f32_16x16x32_bf16 v[36:39], v[174:177], v[206:209], v[36:39]
	v_mfma_f32_16x16x32_bf16 v[20:23], v[174:177], v[214:217], v[20:23]
	v_mfma_f32_16x16x32_bf16 v[20:23], v[186:189], v[218:221], v[20:23]
	v_mfma_f32_16x16x32_bf16 v[16:19], v[194:197], v[218:221], v[16:19]
	v_mfma_f32_16x16x32_bf16 v[16:19], v[190:193], v[214:217], v[16:19]
	v_mfma_f32_16x16x32_bf16 v[0:3], v[190:193], v[222:225], v[0:3]
	v_mfma_f32_16x16x32_bf16 v[0:3], v[194:197], v[226:229], v[0:3]
	v_mfma_f32_16x16x32_bf16 v[4:7], v[186:189], v[226:229], v[4:7]
	v_mfma_f32_16x16x32_bf16 v[4:7], v[174:177], v[222:225], v[4:7]
	s_barrier
	s_add_i32 s55, s55, 2
	s_add_u32 s20, s20, 0x100
	s_addc_u32 s21, s21, 0
	s_add_u32 s53, s53, 0x100
	s_addc_u32 s54, s54, 0
	s_cmpk_gt_u32 s55, 0x55
	s_cbranch_scc0 .LBB0_1361
	s_setprio 0
	s_and_b64 vcc, exec, s[16:17]
	s_cbranch_vccz .LBB0_1364
	s_barrier
